# fused-LN apply hand-written for every LayerNorm but the last (straight-line per variant, one address add per row); unreachable compiler blocks removed
# speedup vs baseline: 1.0013x; 1.0013x over previous
; __device__ __forceinline__ u32x4 pk8(const f32x4 v0, const f32x4 v1) { u32x4 w; w.x = pk_f16(v0[0], v0[1]); w.y = pk_f16(v0[2], v0[3]); w.z = pk_f16(v1[0], v1[1]); w.w = pk_f16(v1[2], v1[3]); return w; }
; __device__ __forceinline__ f32x4 sig4(const f32x4 v) { return (f32x4){sigmoidf_(v[0]), sigmoidf_(v[1]), sigmoidf_(v[2]), sigmoidf_(v[3])}; }
;     __device__ __forceinline__ void operator()(const f32x4 (&acc)[2][2][4][2], const GUnit& u, int wr, int wc, int fr, int fq, LAS unsigned char*) const {
;     ...
; #pragma unroll
;         for (int ai = 0; ai < 2; ++ai)
; #pragma unroll
;             for (int m = 0; m < 4; ++m) { unsigned char* rowp = base + (size_t)(grow0 + ai * 128 + m * 16) * 2048 + (gcol0 - 2048);
;                 if (qk) { f16* qp = (f16*)(ws + (u.kind == K_Q ? B_Q : B_K)) + (size_t)(grow0 + ai * 128 + m * 16) * 512 + (gcol0 & 511);
; #pragma unroll
;                     for (int bj = 0; bj < 2; ++bj) *(u32x4*)(qp + bj * 128) = pk8(acc[ai][bj][m][0] + bv[bj][0], acc[ai][bj][m][1] + bv[bj][1]);
;                     continue; }
; #pragma unroll
;                 for (int bj = 0; bj < 2; ++bj) { f32x4 v0 = sig4(acc[ai][bj][m][0] + bv[bj][0]) * 255.0f, v1 = sig4(acc[ai][bj][m][1] + bv[bj][1]) * 255.0f; u32x2 o = {0u, 0u};
;                     o.x = __builtin_amdgcn_cvt_pk_u8_f32(v0[0], 0, o.x); o.x = __builtin_amdgcn_cvt_pk_u8_f32(v0[1], 1, o.x); o.x = __builtin_amdgcn_cvt_pk_u8_f32(v0[2], 2, o.x); o.x = __builtin_amdgcn_cvt_pk_u8_f32(v0[3], 3, o.x);
;                     o.y = __builtin_amdgcn_cvt_pk_u8_f32(v1[0], 0, o.y); o.y = __builtin_amdgcn_cvt_pk_u8_f32(v1[1], 1, o.y); o.y = __builtin_amdgcn_cvt_pk_u8_f32(v1[2], 2, o.y); o.y = __builtin_amdgcn_cvt_pk_u8_f32(v1[3], 3, o.y);
;                     *(u32x2*)(rowp + bj * 128) = o; } }
.LBB0_78:
	s_andn2_b64 vcc, exec, s[8:9]
	v_lshl_add_u64 v[16:17], s[54:55], 0, v[16:17]
	s_cbranch_vccnz .LBB0_80
.LBB0_80:
	v_or_b32_e32 v26, 16, v18
	v_cndmask_b32_e64 v19, 0, 1, s[24:25]
	v_ashrrev_i32_e32 v27, 31, v26
	s_mov_b64 s[26:27], -1
	v_cmp_ne_u32_e64 s[8:9], 1, v19
	s_andn2_b64 vcc, exec, s[24:25]
	v_pk_add_f32 v[28:29], v[150:151], v[12:13]
	v_pk_add_f32 v[24:25], v[146:147], v[8:9]
	v_pk_add_f32 v[22:23], v[118:119], v[4:5]
	v_pk_add_f32 v[20:21], v[114:115], v[0:1]
	s_cbranch_vccnz .LBB0_82
	s_cmp_eq_u32 s28, 0
	s_cselect_b32 s24, s65, 0x7c00000
	s_add_u32 s24, s54, s24
	s_addc_u32 s25, s55, 0
	v_lshlrev_b64 v[30:31], 10, v[26:27]
	v_lshl_add_u64 v[30:31], s[24:25], 0, v[30:31]
	v_pk_add_f32 v[170:171], v[152:153], v[14:15]
	v_pk_add_f32 v[172:173], v[148:149], v[10:11]
	v_lshl_add_u64 v[30:31], v[30:31], 0, v[32:33]
	v_cvt_pk_f16_f32 v168, v28, v29
	v_cvt_pk_f16_f32 v169, v170, v171
	v_cvt_pk_f16_f32 v170, v24, v25
	v_cvt_pk_f16_f32 v171, v172, v173
	global_store_dwordx4 v[30:31], v[168:171], off
	v_pk_add_f32 v[172:173], v[116:117], v[2:3]
	s_mov_b64 s[26:27], 0
	v_pk_add_f32 v[170:171], v[120:121], v[6:7]
	v_cvt_pk_f16_f32 v168, v22, v23
	v_cvt_pk_f16_f32 v169, v170, v171
	v_cvt_pk_f16_f32 v170, v20, v21
	v_cvt_pk_f16_f32 v171, v172, v173
	global_store_dwordx4 v[30:31], v[168:171], off offset:256
.LBB0_82:
	s_andn2_b64 vcc, exec, s[26:27]
	s_cbranch_vccnz .LBB0_84
.LBB0_84:
	v_or_b32_e32 v26, 32, v18
	v_ashrrev_i32_e32 v27, 31, v26
	s_mov_b64 s[24:25], -1
	s_and_b64 vcc, exec, s[8:9]
	v_pk_add_f32 v[28:29], v[142:143], v[12:13]
	v_pk_add_f32 v[24:25], v[138:139], v[8:9]
	v_pk_add_f32 v[22:23], v[110:111], v[4:5]
	v_pk_add_f32 v[20:21], v[106:107], v[0:1]
	s_cbranch_vccnz .LBB0_86
	s_cmp_eq_u32 s28, 0
	s_cselect_b32 s24, s65, 0x7c00000
	s_add_u32 s24, s54, s24
	s_addc_u32 s25, s55, 0
	v_lshlrev_b64 v[30:31], 10, v[26:27]
	v_lshl_add_u64 v[30:31], s[24:25], 0, v[30:31]
	v_pk_add_f32 v[170:171], v[144:145], v[14:15]
	v_pk_add_f32 v[172:173], v[140:141], v[10:11]
	v_lshl_add_u64 v[30:31], v[30:31], 0, v[32:33]
	v_cvt_pk_f16_f32 v168, v28, v29
	v_cvt_pk_f16_f32 v169, v170, v171
	v_cvt_pk_f16_f32 v170, v24, v25
	v_cvt_pk_f16_f32 v171, v172, v173
	global_store_dwordx4 v[30:31], v[168:171], off
	v_pk_add_f32 v[172:173], v[108:109], v[2:3]
	s_mov_b64 s[24:25], 0
	v_pk_add_f32 v[170:171], v[112:113], v[6:7]
	v_cvt_pk_f16_f32 v168, v22, v23
	v_cvt_pk_f16_f32 v169, v170, v171
	v_cvt_pk_f16_f32 v170, v20, v21
	v_cvt_pk_f16_f32 v171, v172, v173
	global_store_dwordx4 v[30:31], v[168:171], off offset:256
.LBB0_86:
	s_andn2_b64 vcc, exec, s[24:25]
	s_cbranch_vccnz .LBB0_88
.LBB0_88:
	v_or_b32_e32 v26, 48, v18
	v_ashrrev_i32_e32 v27, 31, v26
	s_mov_b64 s[24:25], -1
	s_and_b64 vcc, exec, s[8:9]
	v_pk_add_f32 v[28:29], v[134:135], v[12:13]
	v_pk_add_f32 v[24:25], v[130:131], v[8:9]
	v_pk_add_f32 v[22:23], v[102:103], v[4:5]
	v_pk_add_f32 v[20:21], v[98:99], v[0:1]
	s_cbranch_vccnz .LBB0_90
	s_cmp_eq_u32 s28, 0
	s_cselect_b32 s24, s65, 0x7c00000
	s_add_u32 s24, s54, s24
	s_addc_u32 s25, s55, 0
	v_lshlrev_b64 v[30:31], 10, v[26:27]
	v_lshl_add_u64 v[30:31], s[24:25], 0, v[30:31]
	v_pk_add_f32 v[170:171], v[136:137], v[14:15]
	v_pk_add_f32 v[172:173], v[132:133], v[10:11]
	v_lshl_add_u64 v[30:31], v[30:31], 0, v[32:33]
	v_cvt_pk_f16_f32 v168, v28, v29
	v_cvt_pk_f16_f32 v169, v170, v171
	v_cvt_pk_f16_f32 v170, v24, v25
	v_cvt_pk_f16_f32 v171, v172, v173
	global_store_dwordx4 v[30:31], v[168:171], off
	v_pk_add_f32 v[172:173], v[100:101], v[2:3]
	s_mov_b64 s[24:25], 0
	v_pk_add_f32 v[170:171], v[104:105], v[6:7]
	v_cvt_pk_f16_f32 v168, v22, v23
	v_cvt_pk_f16_f32 v169, v170, v171
	v_cvt_pk_f16_f32 v170, v20, v21
	v_cvt_pk_f16_f32 v171, v172, v173
	global_store_dwordx4 v[30:31], v[168:171], off offset:256
; __device__ __forceinline__ u32x4 pk8(const f32x4 v0, const f32x4 v1) { u32x4 w; w.x = pk_f16(v0[0], v0[1]); w.y = pk_f16(v0[2], v0[3]); w.z = pk_f16(v1[0], v1[1]); w.w = pk_f16(v1[2], v1[3]); return w; }
; __device__ __forceinline__ f32x4 sig4(const f32x4 v) { return (f32x4){sigmoidf_(v[0]), sigmoidf_(v[1]), sigmoidf_(v[2]), sigmoidf_(v[3])}; }
;     __device__ __forceinline__ void operator()(const f32x4 (&acc)[2][2][4][2], const GUnit& u, int wr, int wc, int fr, int fq, LAS unsigned char*) const {
;     ...
; #pragma unroll
;         for (int ai = 0; ai < 2; ++ai)
; #pragma unroll
;             for (int m = 0; m < 4; ++m) { unsigned char* rowp = base + (size_t)(grow0 + ai * 128 + m * 16) * 2048 + (gcol0 - 2048);
;                 if (qk) { f16* qp = (f16*)(ws + (u.kind == K_Q ? B_Q : B_K)) + (size_t)(grow0 + ai * 128 + m * 16) * 512 + (gcol0 & 511);
; #pragma unroll
;                     for (int bj = 0; bj < 2; ++bj) *(u32x4*)(qp + bj * 128) = pk8(acc[ai][bj][m][0] + bv[bj][0], acc[ai][bj][m][1] + bv[bj][1]);
;                     continue; }
; #pragma unroll
;                 for (int bj = 0; bj < 2; ++bj) { f32x4 v0 = sig4(acc[ai][bj][m][0] + bv[bj][0]) * 255.0f, v1 = sig4(acc[ai][bj][m][1] + bv[bj][1]) * 255.0f; u32x2 o = {0u, 0u};
;                     o.x = __builtin_amdgcn_cvt_pk_u8_f32(v0[0], 0, o.x); o.x = __builtin_amdgcn_cvt_pk_u8_f32(v0[1], 1, o.x); o.x = __builtin_amdgcn_cvt_pk_u8_f32(v0[2], 2, o.x); o.x = __builtin_amdgcn_cvt_pk_u8_f32(v0[3], 3, o.x);
;                     o.y = __builtin_amdgcn_cvt_pk_u8_f32(v1[0], 0, o.y); o.y = __builtin_amdgcn_cvt_pk_u8_f32(v1[1], 1, o.y); o.y = __builtin_amdgcn_cvt_pk_u8_f32(v1[2], 2, o.y); o.y = __builtin_amdgcn_cvt_pk_u8_f32(v1[3], 3, o.y);
;                     *(u32x2*)(rowp + bj * 128) = o; } }
.LBB0_90:
	s_andn2_b64 vcc, exec, s[24:25]
	s_cbranch_vccnz .LBB0_92
.LBB0_92:
	v_add_u32_e32 v26, 0x80, v18
	v_ashrrev_i32_e32 v27, 31, v26
	s_mov_b64 s[24:25], -1
	s_and_b64 vcc, exec, s[8:9]
	v_pk_add_f32 v[28:29], v[94:95], v[12:13]
	v_pk_add_f32 v[24:25], v[90:91], v[8:9]
	v_pk_add_f32 v[22:23], v[62:63], v[4:5]
	v_pk_add_f32 v[20:21], v[58:59], v[0:1]
	s_cbranch_vccnz .LBB0_94
	s_cmp_eq_u32 s28, 0
	s_cselect_b32 s24, s65, 0x7c00000
	s_add_u32 s24, s54, s24
	s_addc_u32 s25, s55, 0
	v_lshlrev_b64 v[30:31], 10, v[26:27]
	v_lshl_add_u64 v[30:31], s[24:25], 0, v[30:31]
	v_pk_add_f32 v[170:171], v[96:97], v[14:15]
	v_pk_add_f32 v[172:173], v[92:93], v[10:11]
	v_lshl_add_u64 v[30:31], v[30:31], 0, v[32:33]
	v_cvt_pk_f16_f32 v168, v28, v29
	v_cvt_pk_f16_f32 v169, v170, v171
	v_cvt_pk_f16_f32 v170, v24, v25
	v_cvt_pk_f16_f32 v171, v172, v173
	global_store_dwordx4 v[30:31], v[168:171], off
	v_pk_add_f32 v[172:173], v[60:61], v[2:3]
	s_mov_b64 s[24:25], 0
	v_pk_add_f32 v[170:171], v[64:65], v[6:7]
	v_cvt_pk_f16_f32 v168, v22, v23
	v_cvt_pk_f16_f32 v169, v170, v171
	v_cvt_pk_f16_f32 v170, v20, v21
	v_cvt_pk_f16_f32 v171, v172, v173
	global_store_dwordx4 v[30:31], v[168:171], off offset:256
.LBB0_94:
	s_andn2_b64 vcc, exec, s[24:25]
	s_cbranch_vccnz .LBB0_96
.LBB0_96:
	v_add_u32_e32 v26, 0x90, v18
	v_ashrrev_i32_e32 v27, 31, v26
	s_mov_b64 s[24:25], -1
	s_and_b64 vcc, exec, s[8:9]
	v_pk_add_f32 v[28:29], v[86:87], v[12:13]
	v_pk_add_f32 v[24:25], v[82:83], v[8:9]
	v_pk_add_f32 v[22:23], v[54:55], v[4:5]
	v_pk_add_f32 v[20:21], v[50:51], v[0:1]
	s_cbranch_vccnz .LBB0_98
	s_cmp_eq_u32 s28, 0
	s_cselect_b32 s24, s65, 0x7c00000
	s_add_u32 s24, s54, s24
	s_addc_u32 s25, s55, 0
	v_lshlrev_b64 v[30:31], 10, v[26:27]
	v_lshl_add_u64 v[30:31], s[24:25], 0, v[30:31]
	v_pk_add_f32 v[170:171], v[88:89], v[14:15]
	v_pk_add_f32 v[172:173], v[84:85], v[10:11]
	v_lshl_add_u64 v[30:31], v[30:31], 0, v[32:33]
	v_cvt_pk_f16_f32 v168, v28, v29
	v_cvt_pk_f16_f32 v169, v170, v171
	v_cvt_pk_f16_f32 v170, v24, v25
	v_cvt_pk_f16_f32 v171, v172, v173
	global_store_dwordx4 v[30:31], v[168:171], off
	v_pk_add_f32 v[172:173], v[52:53], v[2:3]
	s_mov_b64 s[24:25], 0
	v_pk_add_f32 v[170:171], v[56:57], v[6:7]
	v_cvt_pk_f16_f32 v168, v22, v23
	v_cvt_pk_f16_f32 v169, v170, v171
	v_cvt_pk_f16_f32 v170, v20, v21
	v_cvt_pk_f16_f32 v171, v172, v173
	global_store_dwordx4 v[30:31], v[168:171], off offset:256
.LBB0_98:
	s_andn2_b64 vcc, exec, s[24:25]
	s_cbranch_vccnz .LBB0_100
.LBB0_100:
	v_add_u32_e32 v26, 0xa0, v18
	v_ashrrev_i32_e32 v27, 31, v26
	s_mov_b64 s[24:25], -1
	s_and_b64 vcc, exec, s[8:9]
	v_pk_add_f32 v[28:29], v[78:79], v[12:13]
	v_pk_add_f32 v[24:25], v[74:75], v[8:9]
	v_pk_add_f32 v[22:23], v[46:47], v[4:5]
	v_pk_add_f32 v[20:21], v[42:43], v[0:1]
	s_cbranch_vccnz .LBB0_102
	s_cmp_eq_u32 s28, 0
	s_cselect_b32 s24, s65, 0x7c00000
	s_add_u32 s24, s54, s24
	s_addc_u32 s25, s55, 0
	v_lshlrev_b64 v[30:31], 10, v[26:27]
	v_lshl_add_u64 v[30:31], s[24:25], 0, v[30:31]
	v_pk_add_f32 v[170:171], v[80:81], v[14:15]
	v_pk_add_f32 v[172:173], v[76:77], v[10:11]
	v_lshl_add_u64 v[30:31], v[30:31], 0, v[32:33]
	v_cvt_pk_f16_f32 v168, v28, v29
	v_cvt_pk_f16_f32 v169, v170, v171
	v_cvt_pk_f16_f32 v170, v24, v25
	v_cvt_pk_f16_f32 v171, v172, v173
	global_store_dwordx4 v[30:31], v[168:171], off
	v_pk_add_f32 v[172:173], v[44:45], v[2:3]
	s_mov_b64 s[24:25], 0
	v_pk_add_f32 v[170:171], v[48:49], v[6:7]
	v_cvt_pk_f16_f32 v168, v22, v23
	v_cvt_pk_f16_f32 v169, v170, v171
	v_cvt_pk_f16_f32 v170, v20, v21
	v_cvt_pk_f16_f32 v171, v172, v173
	global_store_dwordx4 v[30:31], v[168:171], off offset:256

; template <unsigned D> __device__ __forceinline__ u32x4 rd8(u32x4 w) { w.x = rd<D>(w.x); w.y = rd<D>(w.y); w.z = rd<D>(w.z); w.w = rd<D>(w.w); return w; }
; __device__ __forceinline__ u32x4 pk8(const f32x4 v0, const f32x4 v1) { u32x4 w; w.x = pk_f16(v0[0], v0[1]); w.y = pk_f16(v0[2], v0[3]); w.z = pk_f16(v1[0], v1[1]); w.w = pk_f16(v1[2], v1[3]); return w; }
; __device__ __forceinline__ unsigned pk4_fp8(float a, float b, float c, float d) { int w = __builtin_amdgcn_cvt_pk_fp8_f32(a, b, 0, false); w = __builtin_amdgcn_cvt_pk_fp8_f32(c, d, w, true); return (unsigned)w; }
;     __device__ __forceinline__ void fused(f32x4 (&acc)[2][2][4][2], const GUnit& u, int wr, int wc, int fr, int fq, LAS unsigned char* lds, int wid, int lane) const {
;     ...
; #pragma unroll
;         for (int ai = 0; ai < 2; ++ai)
; #pragma unroll
;             for (int m = 0; m < 4; ++m) { const int r = ai * 128 + wr * 64 + m * 16 + fr; const f32x2 sr = S[r]; const size_t row = (size_t)(u.pm * 256 + r);
; #pragma unroll
;                 for (int bj = 0; bj < 2; ++bj) { const int col = gcol0 + bj * 128;
;                     f32x4 y0 = (acc[ai][bj][m][0] - sr.x) * sr.y * gv[bj][0] + bv[bj][0], y1 = (acc[ai][bj][m][1] - sr.x) * sr.y * gv[bj][1] + bv[bj][1];
;                     if (bad) { y0 = (f32x4){qnan, qnan, qnan, qnan}; y1 = y0; }
;                     if (last) { *(f32x4*)(out + row * 1024 + col) = y0; *(f32x4*)(out + row * 1024 + col + 4) = y1; }
;                     else { *(u32x4*)(H16 + row * 1024 + col) = rd8<D_H>(pk8(y0, y1));
;                            if (h8out) { u32x2 q8v; q8v.x = pk4_fp8(y0[0], y0[1], y0[2], y0[3]); q8v.y = pk4_fp8(y1[0], y1[1], y1[2], y1[3]); *(u32x2*)(ws + WS_H8 + row * 1024 + col) = q8v; } } }
.Lap_mine:
	v_lshl_add_u32 v32, v233, 3, 0
	v_readlane_b32 s2, v253, 4
	v_readlane_b32 s3, v253, 5
	v_cmp_eq_u32_e64 s[100:101], 0, v170
	v_readlane_b32 s6, v252, 26
	v_readlane_b32 s7, v252, 27
	v_lshl_add_u64 v[166:167], s[2:3], 0, v[216:217]
	v_lshl_add_u64 v[166:167], v[198:199], 1, v[166:167]
	v_lshlrev_b64 v[178:179], 10, v[214:215]
	v_lshl_add_u64 v[178:179], s[6:7], 0, v[178:179]
	v_lshl_add_u64 v[178:179], v[178:179], 0, v[198:199]
	s_and_b64 vcc, exec, s[16:17]
	s_cbranch_vccnz .Lap_d
	ds_read_b64 v[168:169], v32 offset:8192
	s_waitcnt vmcnt(0) lgkmcnt(0)
	v_cndmask_b32_e64 v169, v229, v169, s[100:101]
	v_pk_add_f32 v[128:129], v[128:129], v[168:169] op_sel_hi:[1,0] neg_lo:[0,1] neg_hi:[0,1]
	v_pk_add_f32 v[130:131], v[130:131], v[168:169] op_sel_hi:[1,0] neg_lo:[0,1] neg_hi:[0,1]
	v_pk_add_f32 v[124:125], v[124:125], v[168:169] op_sel_hi:[1,0] neg_lo:[0,1] neg_hi:[0,1]
	v_pk_add_f32 v[126:127], v[126:127], v[168:169] op_sel_hi:[1,0] neg_lo:[0,1] neg_hi:[0,1]
	v_pk_mul_f32 v[128:129], v[168:169], v[128:129] op_sel:[1,0]
	v_pk_mul_f32 v[130:131], v[168:169], v[130:131] op_sel:[1,0]
	v_pk_mul_f32 v[124:125], v[168:169], v[124:125] op_sel:[1,0]
	v_pk_mul_f32 v[126:127], v[168:169], v[126:127] op_sel:[1,0]
	v_pk_fma_f32 v[128:129], v[160:161], v[128:129], v[156:157]
	v_pk_fma_f32 v[130:131], v[162:163], v[130:131], v[158:159]
	v_pk_fma_f32 v[124:125], v[148:149], v[124:125], v[152:153]
	v_pk_fma_f32 v[126:127], v[150:151], v[126:127], v[154:155]
	v_cvt_pk_f16_f32 v170, v128, v129
	v_cvt_pk_f16_f32 v171, v130, v131
	v_cvt_pk_f16_f32 v172, v124, v125
	v_cvt_pk_f16_f32 v173, v126, v127
	v_add_u32_e32 v170, 0x20002, v170
	v_add_u32_e32 v171, 0x20002, v171
	v_add_u32_e32 v172, 0x20002, v172
	v_add_u32_e32 v173, 0x20002, v173
	v_and_b32_e32 v170, 0xfffcfffc, v170
	v_and_b32_e32 v171, 0xfffcfffc, v171
	v_and_b32_e32 v172, 0xfffcfffc, v172
	v_and_b32_e32 v173, 0xfffcfffc, v173
	global_store_dwordx4 v[166:167], v[170:173], off
	v_cvt_pk_fp8_f32 v174, v128, v129
	v_cvt_pk_fp8_f32 v175, v124, v125
	v_cvt_pk_fp8_f32 v174, v130, v131 op_sel:[0,0,1]
	v_cvt_pk_fp8_f32 v175, v126, v127 op_sel:[0,0,1]
	global_store_dwordx2 v[178:179], v[174:175], off
	v_pk_add_f32 v[120:121], v[120:121], v[168:169] op_sel_hi:[1,0] neg_lo:[0,1] neg_hi:[0,1]
	v_pk_add_f32 v[122:123], v[122:123], v[168:169] op_sel_hi:[1,0] neg_lo:[0,1] neg_hi:[0,1]
	v_pk_add_f32 v[116:117], v[116:117], v[168:169] op_sel_hi:[1,0] neg_lo:[0,1] neg_hi:[0,1]
	v_pk_add_f32 v[118:119], v[118:119], v[168:169] op_sel_hi:[1,0] neg_lo:[0,1] neg_hi:[0,1]
	v_pk_mul_f32 v[120:121], v[168:169], v[120:121] op_sel:[1,0]
	v_pk_mul_f32 v[122:123], v[168:169], v[122:123] op_sel:[1,0]
	v_pk_mul_f32 v[116:117], v[168:169], v[116:117] op_sel:[1,0]
	v_pk_mul_f32 v[118:119], v[168:169], v[118:119] op_sel:[1,0]
	v_pk_fma_f32 v[120:121], v[140:141], v[120:121], v[144:145]
	v_pk_fma_f32 v[122:123], v[142:143], v[122:123], v[146:147]
	v_pk_fma_f32 v[116:117], v[132:133], v[116:117], v[136:137]
	v_pk_fma_f32 v[118:119], v[134:135], v[118:119], v[138:139]
	v_cvt_pk_f16_f32 v170, v120, v121
	v_cvt_pk_f16_f32 v171, v122, v123
	v_cvt_pk_f16_f32 v172, v116, v117
	v_cvt_pk_f16_f32 v173, v118, v119
	v_add_u32_e32 v170, 0x20002, v170
	v_add_u32_e32 v171, 0x20002, v171
	v_add_u32_e32 v172, 0x20002, v172
	v_add_u32_e32 v173, 0x20002, v173
	v_and_b32_e32 v170, 0xfffcfffc, v170
	v_and_b32_e32 v171, 0xfffcfffc, v171
	v_and_b32_e32 v172, 0xfffcfffc, v172
	v_and_b32_e32 v173, 0xfffcfffc, v173
	global_store_dwordx4 v[166:167], v[170:173], off offset:256
	v_cvt_pk_fp8_f32 v174, v120, v121
	v_cvt_pk_fp8_f32 v175, v116, v117
	v_cvt_pk_fp8_f32 v174, v122, v123 op_sel:[0,0,1]
	v_cvt_pk_fp8_f32 v175, v118, v119 op_sel:[0,0,1]
	global_store_dwordx2 v[178:179], v[174:175], off offset:128
	ds_read_b64 v[168:169], v32 offset:8320
	v_add_co_u32_e32 v176, vcc, 0x8000, v166
	v_addc_co_u32_e32 v177, vcc, 0, v167, vcc
	v_add_co_u32_e32 v180, vcc, 0x4000, v178
	v_addc_co_u32_e32 v181, vcc, 0, v179, vcc
	s_waitcnt lgkmcnt(0)
	v_cndmask_b32_e64 v169, v229, v169, s[100:101]
	v_pk_add_f32 v[112:113], v[112:113], v[168:169] op_sel_hi:[1,0] neg_lo:[0,1] neg_hi:[0,1]
	v_pk_add_f32 v[114:115], v[114:115], v[168:169] op_sel_hi:[1,0] neg_lo:[0,1] neg_hi:[0,1]
	v_pk_add_f32 v[108:109], v[108:109], v[168:169] op_sel_hi:[1,0] neg_lo:[0,1] neg_hi:[0,1]
	v_pk_add_f32 v[110:111], v[110:111], v[168:169] op_sel_hi:[1,0] neg_lo:[0,1] neg_hi:[0,1]
	v_pk_mul_f32 v[112:113], v[168:169], v[112:113] op_sel:[1,0]
	v_pk_mul_f32 v[114:115], v[168:169], v[114:115] op_sel:[1,0]
	v_pk_mul_f32 v[108:109], v[168:169], v[108:109] op_sel:[1,0]
	v_pk_mul_f32 v[110:111], v[168:169], v[110:111] op_sel:[1,0]
	v_pk_fma_f32 v[112:113], v[160:161], v[112:113], v[156:157]
	v_pk_fma_f32 v[114:115], v[162:163], v[114:115], v[158:159]
	v_pk_fma_f32 v[108:109], v[148:149], v[108:109], v[152:153]
	v_pk_fma_f32 v[110:111], v[150:151], v[110:111], v[154:155]
	v_cvt_pk_f16_f32 v170, v112, v113
	v_cvt_pk_f16_f32 v171, v114, v115
	v_cvt_pk_f16_f32 v172, v108, v109
	v_cvt_pk_f16_f32 v173, v110, v111
	v_add_u32_e32 v170, 0x20002, v170
	v_add_u32_e32 v171, 0x20002, v171
	v_add_u32_e32 v172, 0x20002, v172
	v_add_u32_e32 v173, 0x20002, v173
	v_and_b32_e32 v170, 0xfffcfffc, v170
	v_and_b32_e32 v171, 0xfffcfffc, v171
	v_and_b32_e32 v172, 0xfffcfffc, v172
	v_and_b32_e32 v173, 0xfffcfffc, v173
	global_store_dwordx4 v[176:177], v[170:173], off
	v_cvt_pk_fp8_f32 v174, v112, v113
	v_cvt_pk_fp8_f32 v175, v108, v109
	v_cvt_pk_fp8_f32 v174, v114, v115 op_sel:[0,0,1]
	v_cvt_pk_fp8_f32 v175, v110, v111 op_sel:[0,0,1]
	global_store_dwordx2 v[180:181], v[174:175], off
; template <unsigned D> __device__ __forceinline__ u32x4 rd8(u32x4 w) { w.x = rd<D>(w.x); w.y = rd<D>(w.y); w.z = rd<D>(w.z); w.w = rd<D>(w.w); return w; }
; __device__ __forceinline__ u32x4 pk8(const f32x4 v0, const f32x4 v1) { u32x4 w; w.x = pk_f16(v0[0], v0[1]); w.y = pk_f16(v0[2], v0[3]); w.z = pk_f16(v1[0], v1[1]); w.w = pk_f16(v1[2], v1[3]); return w; }
; __device__ __forceinline__ unsigned pk4_fp8(float a, float b, float c, float d) { int w = __builtin_amdgcn_cvt_pk_fp8_f32(a, b, 0, false); w = __builtin_amdgcn_cvt_pk_fp8_f32(c, d, w, true); return (unsigned)w; }
;     __device__ __forceinline__ void fused(f32x4 (&acc)[2][2][4][2], const GUnit& u, int wr, int wc, int fr, int fq, LAS unsigned char* lds, int wid, int lane) const {
;     ...
; #pragma unroll
;         for (int ai = 0; ai < 2; ++ai)
; #pragma unroll
;             for (int m = 0; m < 4; ++m) { const int r = ai * 128 + wr * 64 + m * 16 + fr; const f32x2 sr = S[r]; const size_t row = (size_t)(u.pm * 256 + r);
; #pragma unroll
;                 for (int bj = 0; bj < 2; ++bj) { const int col = gcol0 + bj * 128;
;                     f32x4 y0 = (acc[ai][bj][m][0] - sr.x) * sr.y * gv[bj][0] + bv[bj][0], y1 = (acc[ai][bj][m][1] - sr.x) * sr.y * gv[bj][1] + bv[bj][1];
;                     if (bad) { y0 = (f32x4){qnan, qnan, qnan, qnan}; y1 = y0; }
;                     if (last) { *(f32x4*)(out + row * 1024 + col) = y0; *(f32x4*)(out + row * 1024 + col + 4) = y1; }
;                     else { *(u32x4*)(H16 + row * 1024 + col) = rd8<D_H>(pk8(y0, y1));
;                            if (h8out) { u32x2 q8v; q8v.x = pk4_fp8(y0[0], y0[1], y0[2], y0[3]); q8v.y = pk4_fp8(y1[0], y1[1], y1[2], y1[3]); *(u32x2*)(ws + WS_H8 + row * 1024 + col) = q8v; } } }
	v_pk_add_f32 v[104:105], v[104:105], v[168:169] op_sel_hi:[1,0] neg_lo:[0,1] neg_hi:[0,1]
	v_pk_add_f32 v[106:107], v[106:107], v[168:169] op_sel_hi:[1,0] neg_lo:[0,1] neg_hi:[0,1]
	v_pk_add_f32 v[100:101], v[100:101], v[168:169] op_sel_hi:[1,0] neg_lo:[0,1] neg_hi:[0,1]
	v_pk_add_f32 v[102:103], v[102:103], v[168:169] op_sel_hi:[1,0] neg_lo:[0,1] neg_hi:[0,1]
	v_pk_mul_f32 v[104:105], v[168:169], v[104:105] op_sel:[1,0]
	v_pk_mul_f32 v[106:107], v[168:169], v[106:107] op_sel:[1,0]
	v_pk_mul_f32 v[100:101], v[168:169], v[100:101] op_sel:[1,0]
	v_pk_mul_f32 v[102:103], v[168:169], v[102:103] op_sel:[1,0]
	v_pk_fma_f32 v[104:105], v[140:141], v[104:105], v[144:145]
	v_pk_fma_f32 v[106:107], v[142:143], v[106:107], v[146:147]
	v_pk_fma_f32 v[100:101], v[132:133], v[100:101], v[136:137]
	v_pk_fma_f32 v[102:103], v[134:135], v[102:103], v[138:139]
	v_cvt_pk_f16_f32 v170, v104, v105
	v_cvt_pk_f16_f32 v171, v106, v107
	v_cvt_pk_f16_f32 v172, v100, v101
	v_cvt_pk_f16_f32 v173, v102, v103
	v_add_u32_e32 v170, 0x20002, v170
	v_add_u32_e32 v171, 0x20002, v171
	v_add_u32_e32 v172, 0x20002, v172
	v_add_u32_e32 v173, 0x20002, v173
	v_and_b32_e32 v170, 0xfffcfffc, v170
	v_and_b32_e32 v171, 0xfffcfffc, v171
	v_and_b32_e32 v172, 0xfffcfffc, v172
	v_and_b32_e32 v173, 0xfffcfffc, v173
	global_store_dwordx4 v[176:177], v[170:173], off offset:256
	v_cvt_pk_fp8_f32 v174, v104, v105
	v_cvt_pk_fp8_f32 v175, v100, v101
	v_cvt_pk_fp8_f32 v174, v106, v107 op_sel:[0,0,1]
	v_cvt_pk_fp8_f32 v175, v102, v103 op_sel:[0,0,1]
	global_store_dwordx2 v[180:181], v[174:175], off offset:128
	ds_read_b64 v[168:169], v32 offset:8448
	v_add_co_u32_e32 v176, vcc, 0x10000, v166
	v_addc_co_u32_e32 v177, vcc, 0, v167, vcc
	v_add_co_u32_e32 v180, vcc, 0x8000, v178
	v_addc_co_u32_e32 v181, vcc, 0, v179, vcc
	s_waitcnt lgkmcnt(0)
	v_cndmask_b32_e64 v169, v229, v169, s[100:101]
	v_pk_add_f32 v[96:97], v[96:97], v[168:169] op_sel_hi:[1,0] neg_lo:[0,1] neg_hi:[0,1]
	v_pk_add_f32 v[98:99], v[98:99], v[168:169] op_sel_hi:[1,0] neg_lo:[0,1] neg_hi:[0,1]
	v_pk_add_f32 v[92:93], v[92:93], v[168:169] op_sel_hi:[1,0] neg_lo:[0,1] neg_hi:[0,1]
	v_pk_add_f32 v[94:95], v[94:95], v[168:169] op_sel_hi:[1,0] neg_lo:[0,1] neg_hi:[0,1]
	v_pk_mul_f32 v[96:97], v[168:169], v[96:97] op_sel:[1,0]
	v_pk_mul_f32 v[98:99], v[168:169], v[98:99] op_sel:[1,0]
	v_pk_mul_f32 v[92:93], v[168:169], v[92:93] op_sel:[1,0]
	v_pk_mul_f32 v[94:95], v[168:169], v[94:95] op_sel:[1,0]
	v_pk_fma_f32 v[96:97], v[160:161], v[96:97], v[156:157]
	v_pk_fma_f32 v[98:99], v[162:163], v[98:99], v[158:159]
	v_pk_fma_f32 v[92:93], v[148:149], v[92:93], v[152:153]
	v_pk_fma_f32 v[94:95], v[150:151], v[94:95], v[154:155]
	v_cvt_pk_f16_f32 v170, v96, v97
	v_cvt_pk_f16_f32 v171, v98, v99
	v_cvt_pk_f16_f32 v172, v92, v93
	v_cvt_pk_f16_f32 v173, v94, v95
	v_add_u32_e32 v170, 0x20002, v170
	v_add_u32_e32 v171, 0x20002, v171
	v_add_u32_e32 v172, 0x20002, v172
	v_add_u32_e32 v173, 0x20002, v173
	v_and_b32_e32 v170, 0xfffcfffc, v170
	v_and_b32_e32 v171, 0xfffcfffc, v171
	v_and_b32_e32 v172, 0xfffcfffc, v172
	v_and_b32_e32 v173, 0xfffcfffc, v173
	global_store_dwordx4 v[176:177], v[170:173], off
	v_cvt_pk_fp8_f32 v174, v96, v97
	v_cvt_pk_fp8_f32 v175, v92, v93
	v_cvt_pk_fp8_f32 v174, v98, v99 op_sel:[0,0,1]
	v_cvt_pk_fp8_f32 v175, v94, v95 op_sel:[0,0,1]
	global_store_dwordx2 v[180:181], v[174:175], off
	v_pk_add_f32 v[88:89], v[88:89], v[168:169] op_sel_hi:[1,0] neg_lo:[0,1] neg_hi:[0,1]
	v_pk_add_f32 v[90:91], v[90:91], v[168:169] op_sel_hi:[1,0] neg_lo:[0,1] neg_hi:[0,1]
	v_pk_add_f32 v[84:85], v[84:85], v[168:169] op_sel_hi:[1,0] neg_lo:[0,1] neg_hi:[0,1]
	v_pk_add_f32 v[86:87], v[86:87], v[168:169] op_sel_hi:[1,0] neg_lo:[0,1] neg_hi:[0,1]
	v_pk_mul_f32 v[88:89], v[168:169], v[88:89] op_sel:[1,0]
	v_pk_mul_f32 v[90:91], v[168:169], v[90:91] op_sel:[1,0]
	v_pk_mul_f32 v[84:85], v[168:169], v[84:85] op_sel:[1,0]
	v_pk_mul_f32 v[86:87], v[168:169], v[86:87] op_sel:[1,0]
	v_pk_fma_f32 v[88:89], v[140:141], v[88:89], v[144:145]
	v_pk_fma_f32 v[90:91], v[142:143], v[90:91], v[146:147]
	v_pk_fma_f32 v[84:85], v[132:133], v[84:85], v[136:137]
	v_pk_fma_f32 v[86:87], v[134:135], v[86:87], v[138:139]
	v_cvt_pk_f16_f32 v170, v88, v89
	v_cvt_pk_f16_f32 v171, v90, v91
	v_cvt_pk_f16_f32 v172, v84, v85
	v_cvt_pk_f16_f32 v173, v86, v87
	v_add_u32_e32 v170, 0x20002, v170
	v_add_u32_e32 v171, 0x20002, v171
	v_add_u32_e32 v172, 0x20002, v172
	v_add_u32_e32 v173, 0x20002, v173
	v_and_b32_e32 v170, 0xfffcfffc, v170
	v_and_b32_e32 v171, 0xfffcfffc, v171
	v_and_b32_e32 v172, 0xfffcfffc, v172
	v_and_b32_e32 v173, 0xfffcfffc, v173
	global_store_dwordx4 v[176:177], v[170:173], off offset:256
	v_cvt_pk_fp8_f32 v174, v88, v89
	v_cvt_pk_fp8_f32 v175, v84, v85
	v_cvt_pk_fp8_f32 v174, v90, v91 op_sel:[0,0,1]
	v_cvt_pk_fp8_f32 v175, v86, v87 op_sel:[0,0,1]
	global_store_dwordx2 v[180:181], v[174:175], off offset:128
	ds_read_b64 v[168:169], v32 offset:8576
	v_add_co_u32_e32 v176, vcc, 0x18000, v166
	v_addc_co_u32_e32 v177, vcc, 0, v167, vcc
	v_add_co_u32_e32 v180, vcc, 0xc000, v178
	v_addc_co_u32_e32 v181, vcc, 0, v179, vcc
	s_waitcnt lgkmcnt(0)
; template <unsigned D> __device__ __forceinline__ u32x4 rd8(u32x4 w) { w.x = rd<D>(w.x); w.y = rd<D>(w.y); w.z = rd<D>(w.z); w.w = rd<D>(w.w); return w; }
; __device__ __forceinline__ u32x4 pk8(const f32x4 v0, const f32x4 v1) { u32x4 w; w.x = pk_f16(v0[0], v0[1]); w.y = pk_f16(v0[2], v0[3]); w.z = pk_f16(v1[0], v1[1]); w.w = pk_f16(v1[2], v1[3]); return w; }
; __device__ __forceinline__ unsigned pk4_fp8(float a, float b, float c, float d) { int w = __builtin_amdgcn_cvt_pk_fp8_f32(a, b, 0, false); w = __builtin_amdgcn_cvt_pk_fp8_f32(c, d, w, true); return (unsigned)w; }
;     __device__ __forceinline__ void fused(f32x4 (&acc)[2][2][4][2], const GUnit& u, int wr, int wc, int fr, int fq, LAS unsigned char* lds, int wid, int lane) const {
;     ...
; #pragma unroll
;         for (int ai = 0; ai < 2; ++ai)
; #pragma unroll
;             for (int m = 0; m < 4; ++m) { const int r = ai * 128 + wr * 64 + m * 16 + fr; const f32x2 sr = S[r]; const size_t row = (size_t)(u.pm * 256 + r);
; #pragma unroll
;                 for (int bj = 0; bj < 2; ++bj) { const int col = gcol0 + bj * 128;
;                     f32x4 y0 = (acc[ai][bj][m][0] - sr.x) * sr.y * gv[bj][0] + bv[bj][0], y1 = (acc[ai][bj][m][1] - sr.x) * sr.y * gv[bj][1] + bv[bj][1];
;                     if (bad) { y0 = (f32x4){qnan, qnan, qnan, qnan}; y1 = y0; }
;                     if (last) { *(f32x4*)(out + row * 1024 + col) = y0; *(f32x4*)(out + row * 1024 + col + 4) = y1; }
;                     else { *(u32x4*)(H16 + row * 1024 + col) = rd8<D_H>(pk8(y0, y1));
;                            if (h8out) { u32x2 q8v; q8v.x = pk4_fp8(y0[0], y0[1], y0[2], y0[3]); q8v.y = pk4_fp8(y1[0], y1[1], y1[2], y1[3]); *(u32x2*)(ws + WS_H8 + row * 1024 + col) = q8v; } } }
	v_cndmask_b32_e64 v169, v229, v169, s[100:101]
	v_pk_add_f32 v[80:81], v[80:81], v[168:169] op_sel_hi:[1,0] neg_lo:[0,1] neg_hi:[0,1]
	v_pk_add_f32 v[82:83], v[82:83], v[168:169] op_sel_hi:[1,0] neg_lo:[0,1] neg_hi:[0,1]
	v_pk_add_f32 v[76:77], v[76:77], v[168:169] op_sel_hi:[1,0] neg_lo:[0,1] neg_hi:[0,1]
	v_pk_add_f32 v[78:79], v[78:79], v[168:169] op_sel_hi:[1,0] neg_lo:[0,1] neg_hi:[0,1]
	v_pk_mul_f32 v[80:81], v[168:169], v[80:81] op_sel:[1,0]
	v_pk_mul_f32 v[82:83], v[168:169], v[82:83] op_sel:[1,0]
	v_pk_mul_f32 v[76:77], v[168:169], v[76:77] op_sel:[1,0]
	v_pk_mul_f32 v[78:79], v[168:169], v[78:79] op_sel:[1,0]
	v_pk_fma_f32 v[80:81], v[160:161], v[80:81], v[156:157]
	v_pk_fma_f32 v[82:83], v[162:163], v[82:83], v[158:159]
	v_pk_fma_f32 v[76:77], v[148:149], v[76:77], v[152:153]
	v_pk_fma_f32 v[78:79], v[150:151], v[78:79], v[154:155]
	v_cvt_pk_f16_f32 v170, v80, v81
	v_cvt_pk_f16_f32 v171, v82, v83
	v_cvt_pk_f16_f32 v172, v76, v77
	v_cvt_pk_f16_f32 v173, v78, v79
	v_add_u32_e32 v170, 0x20002, v170
	v_add_u32_e32 v171, 0x20002, v171
	v_add_u32_e32 v172, 0x20002, v172
	v_add_u32_e32 v173, 0x20002, v173
	v_and_b32_e32 v170, 0xfffcfffc, v170
	v_and_b32_e32 v171, 0xfffcfffc, v171
	v_and_b32_e32 v172, 0xfffcfffc, v172
	v_and_b32_e32 v173, 0xfffcfffc, v173
	global_store_dwordx4 v[176:177], v[170:173], off
	v_cvt_pk_fp8_f32 v174, v80, v81
	v_cvt_pk_fp8_f32 v175, v76, v77
	v_cvt_pk_fp8_f32 v174, v82, v83 op_sel:[0,0,1]
	v_cvt_pk_fp8_f32 v175, v78, v79 op_sel:[0,0,1]
	global_store_dwordx2 v[180:181], v[174:175], off
	v_pk_add_f32 v[72:73], v[72:73], v[168:169] op_sel_hi:[1,0] neg_lo:[0,1] neg_hi:[0,1]
	v_pk_add_f32 v[74:75], v[74:75], v[168:169] op_sel_hi:[1,0] neg_lo:[0,1] neg_hi:[0,1]
	v_pk_add_f32 v[68:69], v[68:69], v[168:169] op_sel_hi:[1,0] neg_lo:[0,1] neg_hi:[0,1]
	v_pk_add_f32 v[70:71], v[70:71], v[168:169] op_sel_hi:[1,0] neg_lo:[0,1] neg_hi:[0,1]
	v_pk_mul_f32 v[72:73], v[168:169], v[72:73] op_sel:[1,0]
	v_pk_mul_f32 v[74:75], v[168:169], v[74:75] op_sel:[1,0]
	v_pk_mul_f32 v[68:69], v[168:169], v[68:69] op_sel:[1,0]
	v_pk_mul_f32 v[70:71], v[168:169], v[70:71] op_sel:[1,0]
	v_pk_fma_f32 v[72:73], v[140:141], v[72:73], v[144:145]
	v_pk_fma_f32 v[74:75], v[142:143], v[74:75], v[146:147]
	v_pk_fma_f32 v[68:69], v[132:133], v[68:69], v[136:137]
	v_pk_fma_f32 v[70:71], v[134:135], v[70:71], v[138:139]
	v_cvt_pk_f16_f32 v170, v72, v73
	v_cvt_pk_f16_f32 v171, v74, v75
	v_cvt_pk_f16_f32 v172, v68, v69
	v_cvt_pk_f16_f32 v173, v70, v71
	v_add_u32_e32 v170, 0x20002, v170
	v_add_u32_e32 v171, 0x20002, v171
	v_add_u32_e32 v172, 0x20002, v172
	v_add_u32_e32 v173, 0x20002, v173
	v_and_b32_e32 v170, 0xfffcfffc, v170
	v_and_b32_e32 v171, 0xfffcfffc, v171
	v_and_b32_e32 v172, 0xfffcfffc, v172
	v_and_b32_e32 v173, 0xfffcfffc, v173
	global_store_dwordx4 v[176:177], v[170:173], off offset:256
	v_cvt_pk_fp8_f32 v174, v72, v73
	v_cvt_pk_fp8_f32 v175, v68, v69
	v_cvt_pk_fp8_f32 v174, v74, v75 op_sel:[0,0,1]
	v_cvt_pk_fp8_f32 v175, v70, v71 op_sel:[0,0,1]
	global_store_dwordx2 v[180:181], v[174:175], off offset:128
	ds_read_b64 v[168:169], v32 offset:9216
	v_add_co_u32_e32 v176, vcc, 0x40000, v166
	v_addc_co_u32_e32 v177, vcc, 0, v167, vcc
	v_add_co_u32_e32 v180, vcc, 0x20000, v178
	v_addc_co_u32_e32 v181, vcc, 0, v179, vcc
	s_waitcnt lgkmcnt(0)
	v_cndmask_b32_e64 v169, v229, v169, s[100:101]
	v_pk_add_f32 v[64:65], v[64:65], v[168:169] op_sel_hi:[1,0] neg_lo:[0,1] neg_hi:[0,1]
	v_pk_add_f32 v[66:67], v[66:67], v[168:169] op_sel_hi:[1,0] neg_lo:[0,1] neg_hi:[0,1]
	v_pk_add_f32 v[60:61], v[60:61], v[168:169] op_sel_hi:[1,0] neg_lo:[0,1] neg_hi:[0,1]
	v_pk_add_f32 v[62:63], v[62:63], v[168:169] op_sel_hi:[1,0] neg_lo:[0,1] neg_hi:[0,1]
	v_pk_mul_f32 v[64:65], v[168:169], v[64:65] op_sel:[1,0]
	v_pk_mul_f32 v[66:67], v[168:169], v[66:67] op_sel:[1,0]
	v_pk_mul_f32 v[60:61], v[168:169], v[60:61] op_sel:[1,0]
	v_pk_mul_f32 v[62:63], v[168:169], v[62:63] op_sel:[1,0]
	v_pk_fma_f32 v[64:65], v[160:161], v[64:65], v[156:157]
	v_pk_fma_f32 v[66:67], v[162:163], v[66:67], v[158:159]
	v_pk_fma_f32 v[60:61], v[148:149], v[60:61], v[152:153]
	v_pk_fma_f32 v[62:63], v[150:151], v[62:63], v[154:155]
	v_cvt_pk_f16_f32 v170, v64, v65
	v_cvt_pk_f16_f32 v171, v66, v67
	v_cvt_pk_f16_f32 v172, v60, v61
	v_cvt_pk_f16_f32 v173, v62, v63
	v_add_u32_e32 v170, 0x20002, v170
	v_add_u32_e32 v171, 0x20002, v171
	v_add_u32_e32 v172, 0x20002, v172
	v_add_u32_e32 v173, 0x20002, v173
	v_and_b32_e32 v170, 0xfffcfffc, v170
	v_and_b32_e32 v171, 0xfffcfffc, v171
	v_and_b32_e32 v172, 0xfffcfffc, v172
	v_and_b32_e32 v173, 0xfffcfffc, v173
	global_store_dwordx4 v[176:177], v[170:173], off
	v_cvt_pk_fp8_f32 v174, v64, v65
	v_cvt_pk_fp8_f32 v175, v60, v61
	v_cvt_pk_fp8_f32 v174, v66, v67 op_sel:[0,0,1]
	v_cvt_pk_fp8_f32 v175, v62, v63 op_sel:[0,0,1]
	global_store_dwordx2 v[180:181], v[174:175], off
	v_pk_add_f32 v[56:57], v[56:57], v[168:169] op_sel_hi:[1,0] neg_lo:[0,1] neg_hi:[0,1]
	v_pk_add_f32 v[58:59], v[58:59], v[168:169] op_sel_hi:[1,0] neg_lo:[0,1] neg_hi:[0,1]
	v_pk_add_f32 v[52:53], v[52:53], v[168:169] op_sel_hi:[1,0] neg_lo:[0,1] neg_hi:[0,1]
	v_pk_add_f32 v[54:55], v[54:55], v[168:169] op_sel_hi:[1,0] neg_lo:[0,1] neg_hi:[0,1]
	v_pk_mul_f32 v[56:57], v[168:169], v[56:57] op_sel:[1,0]
	v_pk_mul_f32 v[58:59], v[168:169], v[58:59] op_sel:[1,0]
	v_pk_mul_f32 v[52:53], v[168:169], v[52:53] op_sel:[1,0]
	v_pk_mul_f32 v[54:55], v[168:169], v[54:55] op_sel:[1,0]
	v_pk_fma_f32 v[56:57], v[140:141], v[56:57], v[144:145]
	v_pk_fma_f32 v[58:59], v[142:143], v[58:59], v[146:147]
	v_pk_fma_f32 v[52:53], v[132:133], v[52:53], v[136:137]
	v_pk_fma_f32 v[54:55], v[134:135], v[54:55], v[138:139]
	v_cvt_pk_f16_f32 v170, v56, v57
	v_cvt_pk_f16_f32 v171, v58, v59
	v_cvt_pk_f16_f32 v172, v52, v53
	v_cvt_pk_f16_f32 v173, v54, v55
	v_add_u32_e32 v170, 0x20002, v170
	v_add_u32_e32 v171, 0x20002, v171
	v_add_u32_e32 v172, 0x20002, v172
	v_add_u32_e32 v173, 0x20002, v173
	v_and_b32_e32 v170, 0xfffcfffc, v170
	v_and_b32_e32 v171, 0xfffcfffc, v171
	v_and_b32_e32 v172, 0xfffcfffc, v172
	v_and_b32_e32 v173, 0xfffcfffc, v173
	global_store_dwordx4 v[176:177], v[170:173], off offset:256
	v_cvt_pk_fp8_f32 v174, v56, v57
	v_cvt_pk_fp8_f32 v175, v52, v53
	v_cvt_pk_fp8_f32 v174, v58, v59 op_sel:[0,0,1]
	v_cvt_pk_fp8_f32 v175, v54, v55 op_sel:[0,0,1]
	global_store_dwordx2 v[180:181], v[174:175], off offset:128
	ds_read_b64 v[168:169], v32 offset:9344
	v_add_co_u32_e32 v176, vcc, 0x48000, v166
	v_addc_co_u32_e32 v177, vcc, 0, v167, vcc
	v_add_co_u32_e32 v180, vcc, 0x24000, v178
	v_addc_co_u32_e32 v181, vcc, 0, v179, vcc
	s_waitcnt lgkmcnt(0)
; template <unsigned D> __device__ __forceinline__ u32x4 rd8(u32x4 w) { w.x = rd<D>(w.x); w.y = rd<D>(w.y); w.z = rd<D>(w.z); w.w = rd<D>(w.w); return w; }
; __device__ __forceinline__ u32x4 pk8(const f32x4 v0, const f32x4 v1) { u32x4 w; w.x = pk_f16(v0[0], v0[1]); w.y = pk_f16(v0[2], v0[3]); w.z = pk_f16(v1[0], v1[1]); w.w = pk_f16(v1[2], v1[3]); return w; }
; __device__ __forceinline__ unsigned pk4_fp8(float a, float b, float c, float d) { int w = __builtin_amdgcn_cvt_pk_fp8_f32(a, b, 0, false); w = __builtin_amdgcn_cvt_pk_fp8_f32(c, d, w, true); return (unsigned)w; }
;     __device__ __forceinline__ void fused(f32x4 (&acc)[2][2][4][2], const GUnit& u, int wr, int wc, int fr, int fq, LAS unsigned char* lds, int wid, int lane) const {
;     ...
; #pragma unroll
;         for (int ai = 0; ai < 2; ++ai)
; #pragma unroll
;             for (int m = 0; m < 4; ++m) { const int r = ai * 128 + wr * 64 + m * 16 + fr; const f32x2 sr = S[r]; const size_t row = (size_t)(u.pm * 256 + r);
; #pragma unroll
;                 for (int bj = 0; bj < 2; ++bj) { const int col = gcol0 + bj * 128;
;                     f32x4 y0 = (acc[ai][bj][m][0] - sr.x) * sr.y * gv[bj][0] + bv[bj][0], y1 = (acc[ai][bj][m][1] - sr.x) * sr.y * gv[bj][1] + bv[bj][1];
;                     if (bad) { y0 = (f32x4){qnan, qnan, qnan, qnan}; y1 = y0; }
;                     if (last) { *(f32x4*)(out + row * 1024 + col) = y0; *(f32x4*)(out + row * 1024 + col + 4) = y1; }
;                     else { *(u32x4*)(H16 + row * 1024 + col) = rd8<D_H>(pk8(y0, y1));
;                            if (h8out) { u32x2 q8v; q8v.x = pk4_fp8(y0[0], y0[1], y0[2], y0[3]); q8v.y = pk4_fp8(y1[0], y1[1], y1[2], y1[3]); *(u32x2*)(ws + WS_H8 + row * 1024 + col) = q8v; } } }
	v_cndmask_b32_e64 v169, v229, v169, s[100:101]
	v_pk_add_f32 v[48:49], v[48:49], v[168:169] op_sel_hi:[1,0] neg_lo:[0,1] neg_hi:[0,1]
	v_pk_add_f32 v[50:51], v[50:51], v[168:169] op_sel_hi:[1,0] neg_lo:[0,1] neg_hi:[0,1]
	v_pk_add_f32 v[44:45], v[44:45], v[168:169] op_sel_hi:[1,0] neg_lo:[0,1] neg_hi:[0,1]
	v_pk_add_f32 v[46:47], v[46:47], v[168:169] op_sel_hi:[1,0] neg_lo:[0,1] neg_hi:[0,1]
	v_pk_mul_f32 v[48:49], v[168:169], v[48:49] op_sel:[1,0]
	v_pk_mul_f32 v[50:51], v[168:169], v[50:51] op_sel:[1,0]
	v_pk_mul_f32 v[44:45], v[168:169], v[44:45] op_sel:[1,0]
	v_pk_mul_f32 v[46:47], v[168:169], v[46:47] op_sel:[1,0]
	v_pk_fma_f32 v[48:49], v[160:161], v[48:49], v[156:157]
	v_pk_fma_f32 v[50:51], v[162:163], v[50:51], v[158:159]
	v_pk_fma_f32 v[44:45], v[148:149], v[44:45], v[152:153]
	v_pk_fma_f32 v[46:47], v[150:151], v[46:47], v[154:155]
	v_cvt_pk_f16_f32 v170, v48, v49
	v_cvt_pk_f16_f32 v171, v50, v51
	v_cvt_pk_f16_f32 v172, v44, v45
	v_cvt_pk_f16_f32 v173, v46, v47
	v_add_u32_e32 v170, 0x20002, v170
	v_add_u32_e32 v171, 0x20002, v171
	v_add_u32_e32 v172, 0x20002, v172
	v_add_u32_e32 v173, 0x20002, v173
	v_and_b32_e32 v170, 0xfffcfffc, v170
	v_and_b32_e32 v171, 0xfffcfffc, v171
	v_and_b32_e32 v172, 0xfffcfffc, v172
	v_and_b32_e32 v173, 0xfffcfffc, v173
	global_store_dwordx4 v[176:177], v[170:173], off
	v_cvt_pk_fp8_f32 v174, v48, v49
	v_cvt_pk_fp8_f32 v175, v44, v45
	v_cvt_pk_fp8_f32 v174, v50, v51 op_sel:[0,0,1]
	v_cvt_pk_fp8_f32 v175, v46, v47 op_sel:[0,0,1]
	global_store_dwordx2 v[180:181], v[174:175], off
	v_pk_add_f32 v[40:41], v[40:41], v[168:169] op_sel_hi:[1,0] neg_lo:[0,1] neg_hi:[0,1]
	v_pk_add_f32 v[42:43], v[42:43], v[168:169] op_sel_hi:[1,0] neg_lo:[0,1] neg_hi:[0,1]
	v_pk_add_f32 v[36:37], v[36:37], v[168:169] op_sel_hi:[1,0] neg_lo:[0,1] neg_hi:[0,1]
	v_pk_add_f32 v[38:39], v[38:39], v[168:169] op_sel_hi:[1,0] neg_lo:[0,1] neg_hi:[0,1]
	v_pk_mul_f32 v[40:41], v[168:169], v[40:41] op_sel:[1,0]
	v_pk_mul_f32 v[42:43], v[168:169], v[42:43] op_sel:[1,0]
	v_pk_mul_f32 v[36:37], v[168:169], v[36:37] op_sel:[1,0]
	v_pk_mul_f32 v[38:39], v[168:169], v[38:39] op_sel:[1,0]
	v_pk_fma_f32 v[40:41], v[140:141], v[40:41], v[144:145]
	v_pk_fma_f32 v[42:43], v[142:143], v[42:43], v[146:147]
	v_pk_fma_f32 v[36:37], v[132:133], v[36:37], v[136:137]
	v_pk_fma_f32 v[38:39], v[134:135], v[38:39], v[138:139]
	v_cvt_pk_f16_f32 v170, v40, v41
	v_cvt_pk_f16_f32 v171, v42, v43
	v_cvt_pk_f16_f32 v172, v36, v37
	v_cvt_pk_f16_f32 v173, v38, v39
	v_add_u32_e32 v170, 0x20002, v170
	v_add_u32_e32 v171, 0x20002, v171
	v_add_u32_e32 v172, 0x20002, v172
	v_add_u32_e32 v173, 0x20002, v173
	v_and_b32_e32 v170, 0xfffcfffc, v170
	v_and_b32_e32 v171, 0xfffcfffc, v171
	v_and_b32_e32 v172, 0xfffcfffc, v172
	v_and_b32_e32 v173, 0xfffcfffc, v173
	global_store_dwordx4 v[176:177], v[170:173], off offset:256
	v_cvt_pk_fp8_f32 v174, v40, v41
	v_cvt_pk_fp8_f32 v175, v36, v37
	v_cvt_pk_fp8_f32 v174, v42, v43 op_sel:[0,0,1]
	v_cvt_pk_fp8_f32 v175, v38, v39 op_sel:[0,0,1]
	global_store_dwordx2 v[180:181], v[174:175], off offset:128
	ds_read_b64 v[168:169], v32 offset:9472
	v_add_co_u32_e32 v176, vcc, 0x50000, v166
	v_addc_co_u32_e32 v177, vcc, 0, v167, vcc
	v_add_co_u32_e32 v180, vcc, 0x28000, v178
	v_addc_co_u32_e32 v181, vcc, 0, v179, vcc
	s_waitcnt lgkmcnt(0)
	v_cndmask_b32_e64 v169, v229, v169, s[100:101]
	v_pk_add_f32 v[28:29], v[28:29], v[168:169] op_sel_hi:[1,0] neg_lo:[0,1] neg_hi:[0,1]
	v_pk_add_f32 v[30:31], v[30:31], v[168:169] op_sel_hi:[1,0] neg_lo:[0,1] neg_hi:[0,1]
	v_pk_add_f32 v[24:25], v[24:25], v[168:169] op_sel_hi:[1,0] neg_lo:[0,1] neg_hi:[0,1]
	v_pk_add_f32 v[26:27], v[26:27], v[168:169] op_sel_hi:[1,0] neg_lo:[0,1] neg_hi:[0,1]
	v_pk_mul_f32 v[28:29], v[168:169], v[28:29] op_sel:[1,0]
	v_pk_mul_f32 v[30:31], v[168:169], v[30:31] op_sel:[1,0]
	v_pk_mul_f32 v[24:25], v[168:169], v[24:25] op_sel:[1,0]
	v_pk_mul_f32 v[26:27], v[168:169], v[26:27] op_sel:[1,0]
	v_pk_fma_f32 v[28:29], v[160:161], v[28:29], v[156:157]
	v_pk_fma_f32 v[30:31], v[162:163], v[30:31], v[158:159]
	v_pk_fma_f32 v[24:25], v[148:149], v[24:25], v[152:153]
	v_pk_fma_f32 v[26:27], v[150:151], v[26:27], v[154:155]
	v_cvt_pk_f16_f32 v170, v28, v29
	v_cvt_pk_f16_f32 v171, v30, v31
	v_cvt_pk_f16_f32 v172, v24, v25
	v_cvt_pk_f16_f32 v173, v26, v27
	v_add_u32_e32 v170, 0x20002, v170
	v_add_u32_e32 v171, 0x20002, v171
	v_add_u32_e32 v172, 0x20002, v172
	v_add_u32_e32 v173, 0x20002, v173
	v_and_b32_e32 v170, 0xfffcfffc, v170
	v_and_b32_e32 v171, 0xfffcfffc, v171
	v_and_b32_e32 v172, 0xfffcfffc, v172
	v_and_b32_e32 v173, 0xfffcfffc, v173
	global_store_dwordx4 v[176:177], v[170:173], off
	v_cvt_pk_fp8_f32 v174, v28, v29
	v_cvt_pk_fp8_f32 v175, v24, v25
	v_cvt_pk_fp8_f32 v174, v30, v31 op_sel:[0,0,1]
	v_cvt_pk_fp8_f32 v175, v26, v27 op_sel:[0,0,1]
	global_store_dwordx2 v[180:181], v[174:175], off
	v_pk_add_f32 v[20:21], v[20:21], v[168:169] op_sel_hi:[1,0] neg_lo:[0,1] neg_hi:[0,1]
	v_pk_add_f32 v[22:23], v[22:23], v[168:169] op_sel_hi:[1,0] neg_lo:[0,1] neg_hi:[0,1]
	v_pk_add_f32 v[16:17], v[16:17], v[168:169] op_sel_hi:[1,0] neg_lo:[0,1] neg_hi:[0,1]
	v_pk_add_f32 v[18:19], v[18:19], v[168:169] op_sel_hi:[1,0] neg_lo:[0,1] neg_hi:[0,1]
	v_pk_mul_f32 v[20:21], v[168:169], v[20:21] op_sel:[1,0]
	v_pk_mul_f32 v[22:23], v[168:169], v[22:23] op_sel:[1,0]
	v_pk_mul_f32 v[16:17], v[168:169], v[16:17] op_sel:[1,0]
	v_pk_mul_f32 v[18:19], v[168:169], v[18:19] op_sel:[1,0]
	v_pk_fma_f32 v[20:21], v[140:141], v[20:21], v[144:145]
	v_pk_fma_f32 v[22:23], v[142:143], v[22:23], v[146:147]
	v_pk_fma_f32 v[16:17], v[132:133], v[16:17], v[136:137]
	v_pk_fma_f32 v[18:19], v[134:135], v[18:19], v[138:139]
	v_cvt_pk_f16_f32 v170, v20, v21
	v_cvt_pk_f16_f32 v171, v22, v23
	v_cvt_pk_f16_f32 v172, v16, v17
	v_cvt_pk_f16_f32 v173, v18, v19
	v_add_u32_e32 v170, 0x20002, v170
	v_add_u32_e32 v171, 0x20002, v171
	v_add_u32_e32 v172, 0x20002, v172
	v_add_u32_e32 v173, 0x20002, v173
	v_and_b32_e32 v170, 0xfffcfffc, v170
	v_and_b32_e32 v171, 0xfffcfffc, v171
	v_and_b32_e32 v172, 0xfffcfffc, v172
	v_and_b32_e32 v173, 0xfffcfffc, v173
	global_store_dwordx4 v[176:177], v[170:173], off offset:256
	v_cvt_pk_fp8_f32 v174, v20, v21
	v_cvt_pk_fp8_f32 v175, v16, v17
	v_cvt_pk_fp8_f32 v174, v22, v23 op_sel:[0,0,1]
	v_cvt_pk_fp8_f32 v175, v18, v19 op_sel:[0,0,1]
	global_store_dwordx2 v[180:181], v[174:175], off offset:128
	ds_read_b64 v[168:169], v32 offset:9600
	v_add_co_u32_e32 v176, vcc, 0x58000, v166
	v_addc_co_u32_e32 v177, vcc, 0, v167, vcc
	v_add_co_u32_e32 v180, vcc, 0x2c000, v178
	v_addc_co_u32_e32 v181, vcc, 0, v179, vcc
	s_waitcnt lgkmcnt(0)
; template <unsigned D> __device__ __forceinline__ u32x4 rd8(u32x4 w) { w.x = rd<D>(w.x); w.y = rd<D>(w.y); w.z = rd<D>(w.z); w.w = rd<D>(w.w); return w; }
; __device__ __forceinline__ u32x4 pk8(const f32x4 v0, const f32x4 v1) { u32x4 w; w.x = pk_f16(v0[0], v0[1]); w.y = pk_f16(v0[2], v0[3]); w.z = pk_f16(v1[0], v1[1]); w.w = pk_f16(v1[2], v1[3]); return w; }
; __device__ __forceinline__ unsigned pk4_fp8(float a, float b, float c, float d) { int w = __builtin_amdgcn_cvt_pk_fp8_f32(a, b, 0, false); w = __builtin_amdgcn_cvt_pk_fp8_f32(c, d, w, true); return (unsigned)w; }
;     __device__ __forceinline__ void fused(f32x4 (&acc)[2][2][4][2], const GUnit& u, int wr, int wc, int fr, int fq, LAS unsigned char* lds, int wid, int lane) const {
;     ...
; #pragma unroll
;         for (int ai = 0; ai < 2; ++ai)
; #pragma unroll
;             for (int m = 0; m < 4; ++m) { const int r = ai * 128 + wr * 64 + m * 16 + fr; const f32x2 sr = S[r]; const size_t row = (size_t)(u.pm * 256 + r);
; #pragma unroll
;                 for (int bj = 0; bj < 2; ++bj) { const int col = gcol0 + bj * 128;
;                     f32x4 y0 = (acc[ai][bj][m][0] - sr.x) * sr.y * gv[bj][0] + bv[bj][0], y1 = (acc[ai][bj][m][1] - sr.x) * sr.y * gv[bj][1] + bv[bj][1];
;                     if (bad) { y0 = (f32x4){qnan, qnan, qnan, qnan}; y1 = y0; }
;                     if (last) { *(f32x4*)(out + row * 1024 + col) = y0; *(f32x4*)(out + row * 1024 + col + 4) = y1; }
;                     else { *(u32x4*)(H16 + row * 1024 + col) = rd8<D_H>(pk8(y0, y1));
;                            if (h8out) { u32x2 q8v; q8v.x = pk4_fp8(y0[0], y0[1], y0[2], y0[3]); q8v.y = pk4_fp8(y1[0], y1[1], y1[2], y1[3]); *(u32x2*)(ws + WS_H8 + row * 1024 + col) = q8v; } } }
	v_cndmask_b32_e64 v169, v229, v169, s[100:101]
	v_pk_add_f32 v[12:13], v[12:13], v[168:169] op_sel_hi:[1,0] neg_lo:[0,1] neg_hi:[0,1]
	v_pk_add_f32 v[14:15], v[14:15], v[168:169] op_sel_hi:[1,0] neg_lo:[0,1] neg_hi:[0,1]
	v_pk_add_f32 v[8:9], v[8:9], v[168:169] op_sel_hi:[1,0] neg_lo:[0,1] neg_hi:[0,1]
	v_pk_add_f32 v[10:11], v[10:11], v[168:169] op_sel_hi:[1,0] neg_lo:[0,1] neg_hi:[0,1]
	v_pk_mul_f32 v[12:13], v[168:169], v[12:13] op_sel:[1,0]
	v_pk_mul_f32 v[14:15], v[168:169], v[14:15] op_sel:[1,0]
	v_pk_mul_f32 v[8:9], v[168:169], v[8:9] op_sel:[1,0]
	v_pk_mul_f32 v[10:11], v[168:169], v[10:11] op_sel:[1,0]
	v_pk_fma_f32 v[12:13], v[160:161], v[12:13], v[156:157]
	v_pk_fma_f32 v[14:15], v[162:163], v[14:15], v[158:159]
	v_pk_fma_f32 v[8:9], v[148:149], v[8:9], v[152:153]
	v_pk_fma_f32 v[10:11], v[150:151], v[10:11], v[154:155]
	v_cvt_pk_f16_f32 v170, v12, v13
	v_cvt_pk_f16_f32 v171, v14, v15
	v_cvt_pk_f16_f32 v172, v8, v9
	v_cvt_pk_f16_f32 v173, v10, v11
	v_add_u32_e32 v170, 0x20002, v170
	v_add_u32_e32 v171, 0x20002, v171
	v_add_u32_e32 v172, 0x20002, v172
	v_add_u32_e32 v173, 0x20002, v173
	v_and_b32_e32 v170, 0xfffcfffc, v170
	v_and_b32_e32 v171, 0xfffcfffc, v171
	v_and_b32_e32 v172, 0xfffcfffc, v172
	v_and_b32_e32 v173, 0xfffcfffc, v173
	global_store_dwordx4 v[176:177], v[170:173], off
	v_cvt_pk_fp8_f32 v174, v12, v13
	v_cvt_pk_fp8_f32 v175, v8, v9
	v_cvt_pk_fp8_f32 v174, v14, v15 op_sel:[0,0,1]
	v_cvt_pk_fp8_f32 v175, v10, v11 op_sel:[0,0,1]
	global_store_dwordx2 v[180:181], v[174:175], off
	v_pk_add_f32 v[4:5], v[4:5], v[168:169] op_sel_hi:[1,0] neg_lo:[0,1] neg_hi:[0,1]
	v_pk_add_f32 v[6:7], v[6:7], v[168:169] op_sel_hi:[1,0] neg_lo:[0,1] neg_hi:[0,1]
	v_pk_add_f32 v[0:1], v[0:1], v[168:169] op_sel_hi:[1,0] neg_lo:[0,1] neg_hi:[0,1]
	v_pk_add_f32 v[2:3], v[2:3], v[168:169] op_sel_hi:[1,0] neg_lo:[0,1] neg_hi:[0,1]
	v_pk_mul_f32 v[4:5], v[168:169], v[4:5] op_sel:[1,0]
	v_pk_mul_f32 v[6:7], v[168:169], v[6:7] op_sel:[1,0]
	v_pk_mul_f32 v[0:1], v[168:169], v[0:1] op_sel:[1,0]
	v_pk_mul_f32 v[2:3], v[168:169], v[2:3] op_sel:[1,0]
	v_pk_fma_f32 v[4:5], v[140:141], v[4:5], v[144:145]
	v_pk_fma_f32 v[6:7], v[142:143], v[6:7], v[146:147]
	v_pk_fma_f32 v[0:1], v[132:133], v[0:1], v[136:137]
	v_pk_fma_f32 v[2:3], v[134:135], v[2:3], v[138:139]
	v_cvt_pk_f16_f32 v170, v4, v5
	v_cvt_pk_f16_f32 v171, v6, v7
	v_cvt_pk_f16_f32 v172, v0, v1
	v_cvt_pk_f16_f32 v173, v2, v3
	v_add_u32_e32 v170, 0x20002, v170
	v_add_u32_e32 v171, 0x20002, v171
	v_add_u32_e32 v172, 0x20002, v172
	v_add_u32_e32 v173, 0x20002, v173
	v_and_b32_e32 v170, 0xfffcfffc, v170
	v_and_b32_e32 v171, 0xfffcfffc, v171
	v_and_b32_e32 v172, 0xfffcfffc, v172
	v_and_b32_e32 v173, 0xfffcfffc, v173
	global_store_dwordx4 v[176:177], v[170:173], off offset:256
	v_cvt_pk_fp8_f32 v174, v4, v5
	v_cvt_pk_fp8_f32 v175, v0, v1
	v_cvt_pk_fp8_f32 v174, v6, v7 op_sel:[0,0,1]
	v_cvt_pk_fp8_f32 v175, v2, v3 op_sel:[0,0,1]
	global_store_dwordx2 v[180:181], v[174:175], off offset:128
	v_mov_b32_e32 v233, v226
	s_branch .LBB0_567
.Lap_d:
	ds_read_b64 v[168:169], v32 offset:8192
	s_waitcnt vmcnt(0) lgkmcnt(0)
	v_cndmask_b32_e64 v169, v229, v169, s[100:101]
	v_pk_add_f32 v[128:129], v[128:129], v[168:169] op_sel_hi:[1,0] neg_lo:[0,1] neg_hi:[0,1]
	v_pk_add_f32 v[130:131], v[130:131], v[168:169] op_sel_hi:[1,0] neg_lo:[0,1] neg_hi:[0,1]
	v_pk_add_f32 v[124:125], v[124:125], v[168:169] op_sel_hi:[1,0] neg_lo:[0,1] neg_hi:[0,1]
	v_pk_add_f32 v[126:127], v[126:127], v[168:169] op_sel_hi:[1,0] neg_lo:[0,1] neg_hi:[0,1]
	v_pk_mul_f32 v[128:129], v[168:169], v[128:129] op_sel:[1,0]
	v_pk_mul_f32 v[130:131], v[168:169], v[130:131] op_sel:[1,0]
	v_pk_mul_f32 v[124:125], v[168:169], v[124:125] op_sel:[1,0]
	v_pk_mul_f32 v[126:127], v[168:169], v[126:127] op_sel:[1,0]
	v_pk_fma_f32 v[128:129], v[160:161], v[128:129], v[156:157]
	v_pk_fma_f32 v[130:131], v[162:163], v[130:131], v[158:159]
	v_pk_fma_f32 v[124:125], v[148:149], v[124:125], v[152:153]
	v_pk_fma_f32 v[126:127], v[150:151], v[126:127], v[154:155]
	v_cvt_pk_f16_f32 v170, v128, v129
	v_cvt_pk_f16_f32 v171, v130, v131
	v_cvt_pk_f16_f32 v172, v124, v125
	v_cvt_pk_f16_f32 v173, v126, v127
	v_add_u32_e32 v170, 0x20002, v170
	v_add_u32_e32 v171, 0x20002, v171
	v_add_u32_e32 v172, 0x20002, v172
	v_add_u32_e32 v173, 0x20002, v173
	v_and_b32_e32 v170, 0xfffcfffc, v170
	v_and_b32_e32 v171, 0xfffcfffc, v171
	v_and_b32_e32 v172, 0xfffcfffc, v172
	v_and_b32_e32 v173, 0xfffcfffc, v173
	global_store_dwordx4 v[166:167], v[170:173], off
	v_pk_add_f32 v[120:121], v[120:121], v[168:169] op_sel_hi:[1,0] neg_lo:[0,1] neg_hi:[0,1]
	v_pk_add_f32 v[122:123], v[122:123], v[168:169] op_sel_hi:[1,0] neg_lo:[0,1] neg_hi:[0,1]
	v_pk_add_f32 v[116:117], v[116:117], v[168:169] op_sel_hi:[1,0] neg_lo:[0,1] neg_hi:[0,1]
	v_pk_add_f32 v[118:119], v[118:119], v[168:169] op_sel_hi:[1,0] neg_lo:[0,1] neg_hi:[0,1]
	v_pk_mul_f32 v[120:121], v[168:169], v[120:121] op_sel:[1,0]
	v_pk_mul_f32 v[122:123], v[168:169], v[122:123] op_sel:[1,0]
	v_pk_mul_f32 v[116:117], v[168:169], v[116:117] op_sel:[1,0]
	v_pk_mul_f32 v[118:119], v[168:169], v[118:119] op_sel:[1,0]
	v_pk_fma_f32 v[120:121], v[140:141], v[120:121], v[144:145]
	v_pk_fma_f32 v[122:123], v[142:143], v[122:123], v[146:147]
	v_pk_fma_f32 v[116:117], v[132:133], v[116:117], v[136:137]
	v_pk_fma_f32 v[118:119], v[134:135], v[118:119], v[138:139]
	v_cvt_pk_f16_f32 v170, v120, v121
	v_cvt_pk_f16_f32 v171, v122, v123
	v_cvt_pk_f16_f32 v172, v116, v117
	v_cvt_pk_f16_f32 v173, v118, v119
	v_add_u32_e32 v170, 0x20002, v170
	v_add_u32_e32 v171, 0x20002, v171
	v_add_u32_e32 v172, 0x20002, v172
	v_add_u32_e32 v173, 0x20002, v173
	v_and_b32_e32 v170, 0xfffcfffc, v170
	v_and_b32_e32 v171, 0xfffcfffc, v171
	v_and_b32_e32 v172, 0xfffcfffc, v172
	v_and_b32_e32 v173, 0xfffcfffc, v173
	global_store_dwordx4 v[166:167], v[170:173], off offset:256
	ds_read_b64 v[168:169], v32 offset:8320
	v_add_co_u32_e32 v176, vcc, 0x8000, v166
	v_addc_co_u32_e32 v177, vcc, 0, v167, vcc
	s_waitcnt lgkmcnt(0)
; template <unsigned D> __device__ __forceinline__ u32x4 rd8(u32x4 w) { w.x = rd<D>(w.x); w.y = rd<D>(w.y); w.z = rd<D>(w.z); w.w = rd<D>(w.w); return w; }
; __device__ __forceinline__ u32x4 pk8(const f32x4 v0, const f32x4 v1) { u32x4 w; w.x = pk_f16(v0[0], v0[1]); w.y = pk_f16(v0[2], v0[3]); w.z = pk_f16(v1[0], v1[1]); w.w = pk_f16(v1[2], v1[3]); return w; }
; __device__ __forceinline__ unsigned pk4_fp8(float a, float b, float c, float d) { int w = __builtin_amdgcn_cvt_pk_fp8_f32(a, b, 0, false); w = __builtin_amdgcn_cvt_pk_fp8_f32(c, d, w, true); return (unsigned)w; }
;     __device__ __forceinline__ void fused(f32x4 (&acc)[2][2][4][2], const GUnit& u, int wr, int wc, int fr, int fq, LAS unsigned char* lds, int wid, int lane) const {
;     ...
; #pragma unroll
;         for (int ai = 0; ai < 2; ++ai)
; #pragma unroll
;             for (int m = 0; m < 4; ++m) { const int r = ai * 128 + wr * 64 + m * 16 + fr; const f32x2 sr = S[r]; const size_t row = (size_t)(u.pm * 256 + r);
; #pragma unroll
;                 for (int bj = 0; bj < 2; ++bj) { const int col = gcol0 + bj * 128;
;                     f32x4 y0 = (acc[ai][bj][m][0] - sr.x) * sr.y * gv[bj][0] + bv[bj][0], y1 = (acc[ai][bj][m][1] - sr.x) * sr.y * gv[bj][1] + bv[bj][1];
;                     if (bad) { y0 = (f32x4){qnan, qnan, qnan, qnan}; y1 = y0; }
;                     if (last) { *(f32x4*)(out + row * 1024 + col) = y0; *(f32x4*)(out + row * 1024 + col + 4) = y1; }
;                     else { *(u32x4*)(H16 + row * 1024 + col) = rd8<D_H>(pk8(y0, y1));
;                            if (h8out) { u32x2 q8v; q8v.x = pk4_fp8(y0[0], y0[1], y0[2], y0[3]); q8v.y = pk4_fp8(y1[0], y1[1], y1[2], y1[3]); *(u32x2*)(ws + WS_H8 + row * 1024 + col) = q8v; } } }
	v_cndmask_b32_e64 v169, v229, v169, s[100:101]
	v_pk_add_f32 v[112:113], v[112:113], v[168:169] op_sel_hi:[1,0] neg_lo:[0,1] neg_hi:[0,1]
	v_pk_add_f32 v[114:115], v[114:115], v[168:169] op_sel_hi:[1,0] neg_lo:[0,1] neg_hi:[0,1]
	v_pk_add_f32 v[108:109], v[108:109], v[168:169] op_sel_hi:[1,0] neg_lo:[0,1] neg_hi:[0,1]
	v_pk_add_f32 v[110:111], v[110:111], v[168:169] op_sel_hi:[1,0] neg_lo:[0,1] neg_hi:[0,1]
	v_pk_mul_f32 v[112:113], v[168:169], v[112:113] op_sel:[1,0]
	v_pk_mul_f32 v[114:115], v[168:169], v[114:115] op_sel:[1,0]
	v_pk_mul_f32 v[108:109], v[168:169], v[108:109] op_sel:[1,0]
	v_pk_mul_f32 v[110:111], v[168:169], v[110:111] op_sel:[1,0]
	v_pk_fma_f32 v[112:113], v[160:161], v[112:113], v[156:157]
	v_pk_fma_f32 v[114:115], v[162:163], v[114:115], v[158:159]
	v_pk_fma_f32 v[108:109], v[148:149], v[108:109], v[152:153]
	v_pk_fma_f32 v[110:111], v[150:151], v[110:111], v[154:155]
	v_cvt_pk_f16_f32 v170, v112, v113
	v_cvt_pk_f16_f32 v171, v114, v115
	v_cvt_pk_f16_f32 v172, v108, v109
	v_cvt_pk_f16_f32 v173, v110, v111
	v_add_u32_e32 v170, 0x20002, v170
	v_add_u32_e32 v171, 0x20002, v171
	v_add_u32_e32 v172, 0x20002, v172
	v_add_u32_e32 v173, 0x20002, v173
	v_and_b32_e32 v170, 0xfffcfffc, v170
	v_and_b32_e32 v171, 0xfffcfffc, v171
	v_and_b32_e32 v172, 0xfffcfffc, v172
	v_and_b32_e32 v173, 0xfffcfffc, v173
	global_store_dwordx4 v[176:177], v[170:173], off
	v_pk_add_f32 v[104:105], v[104:105], v[168:169] op_sel_hi:[1,0] neg_lo:[0,1] neg_hi:[0,1]
	v_pk_add_f32 v[106:107], v[106:107], v[168:169] op_sel_hi:[1,0] neg_lo:[0,1] neg_hi:[0,1]
	v_pk_add_f32 v[100:101], v[100:101], v[168:169] op_sel_hi:[1,0] neg_lo:[0,1] neg_hi:[0,1]
	v_pk_add_f32 v[102:103], v[102:103], v[168:169] op_sel_hi:[1,0] neg_lo:[0,1] neg_hi:[0,1]
	v_pk_mul_f32 v[104:105], v[168:169], v[104:105] op_sel:[1,0]
	v_pk_mul_f32 v[106:107], v[168:169], v[106:107] op_sel:[1,0]
	v_pk_mul_f32 v[100:101], v[168:169], v[100:101] op_sel:[1,0]
	v_pk_mul_f32 v[102:103], v[168:169], v[102:103] op_sel:[1,0]
	v_pk_fma_f32 v[104:105], v[140:141], v[104:105], v[144:145]
	v_pk_fma_f32 v[106:107], v[142:143], v[106:107], v[146:147]
	v_pk_fma_f32 v[100:101], v[132:133], v[100:101], v[136:137]
	v_pk_fma_f32 v[102:103], v[134:135], v[102:103], v[138:139]
	v_cvt_pk_f16_f32 v170, v104, v105
	v_cvt_pk_f16_f32 v171, v106, v107
	v_cvt_pk_f16_f32 v172, v100, v101
	v_cvt_pk_f16_f32 v173, v102, v103
	v_add_u32_e32 v170, 0x20002, v170
	v_add_u32_e32 v171, 0x20002, v171
	v_add_u32_e32 v172, 0x20002, v172
	v_add_u32_e32 v173, 0x20002, v173
	v_and_b32_e32 v170, 0xfffcfffc, v170
	v_and_b32_e32 v171, 0xfffcfffc, v171
	v_and_b32_e32 v172, 0xfffcfffc, v172
	v_and_b32_e32 v173, 0xfffcfffc, v173
	global_store_dwordx4 v[176:177], v[170:173], off offset:256
	ds_read_b64 v[168:169], v32 offset:8448
	v_add_co_u32_e32 v176, vcc, 0x10000, v166
	v_addc_co_u32_e32 v177, vcc, 0, v167, vcc
	s_waitcnt lgkmcnt(0)
	v_cndmask_b32_e64 v169, v229, v169, s[100:101]
	v_pk_add_f32 v[96:97], v[96:97], v[168:169] op_sel_hi:[1,0] neg_lo:[0,1] neg_hi:[0,1]
	v_pk_add_f32 v[98:99], v[98:99], v[168:169] op_sel_hi:[1,0] neg_lo:[0,1] neg_hi:[0,1]
	v_pk_add_f32 v[92:93], v[92:93], v[168:169] op_sel_hi:[1,0] neg_lo:[0,1] neg_hi:[0,1]
	v_pk_add_f32 v[94:95], v[94:95], v[168:169] op_sel_hi:[1,0] neg_lo:[0,1] neg_hi:[0,1]
	v_pk_mul_f32 v[96:97], v[168:169], v[96:97] op_sel:[1,0]
	v_pk_mul_f32 v[98:99], v[168:169], v[98:99] op_sel:[1,0]
	v_pk_mul_f32 v[92:93], v[168:169], v[92:93] op_sel:[1,0]
	v_pk_mul_f32 v[94:95], v[168:169], v[94:95] op_sel:[1,0]
	v_pk_fma_f32 v[96:97], v[160:161], v[96:97], v[156:157]
	v_pk_fma_f32 v[98:99], v[162:163], v[98:99], v[158:159]
	v_pk_fma_f32 v[92:93], v[148:149], v[92:93], v[152:153]
	v_pk_fma_f32 v[94:95], v[150:151], v[94:95], v[154:155]
	v_cvt_pk_f16_f32 v170, v96, v97
	v_cvt_pk_f16_f32 v171, v98, v99
	v_cvt_pk_f16_f32 v172, v92, v93
	v_cvt_pk_f16_f32 v173, v94, v95
	v_add_u32_e32 v170, 0x20002, v170
	v_add_u32_e32 v171, 0x20002, v171
	v_add_u32_e32 v172, 0x20002, v172
	v_add_u32_e32 v173, 0x20002, v173
	v_and_b32_e32 v170, 0xfffcfffc, v170
	v_and_b32_e32 v171, 0xfffcfffc, v171
	v_and_b32_e32 v172, 0xfffcfffc, v172
	v_and_b32_e32 v173, 0xfffcfffc, v173
	global_store_dwordx4 v[176:177], v[170:173], off
	v_pk_add_f32 v[88:89], v[88:89], v[168:169] op_sel_hi:[1,0] neg_lo:[0,1] neg_hi:[0,1]
	v_pk_add_f32 v[90:91], v[90:91], v[168:169] op_sel_hi:[1,0] neg_lo:[0,1] neg_hi:[0,1]
	v_pk_add_f32 v[84:85], v[84:85], v[168:169] op_sel_hi:[1,0] neg_lo:[0,1] neg_hi:[0,1]
	v_pk_add_f32 v[86:87], v[86:87], v[168:169] op_sel_hi:[1,0] neg_lo:[0,1] neg_hi:[0,1]
	v_pk_mul_f32 v[88:89], v[168:169], v[88:89] op_sel:[1,0]
	v_pk_mul_f32 v[90:91], v[168:169], v[90:91] op_sel:[1,0]
	v_pk_mul_f32 v[84:85], v[168:169], v[84:85] op_sel:[1,0]
	v_pk_mul_f32 v[86:87], v[168:169], v[86:87] op_sel:[1,0]
	v_pk_fma_f32 v[88:89], v[140:141], v[88:89], v[144:145]
	v_pk_fma_f32 v[90:91], v[142:143], v[90:91], v[146:147]
	v_pk_fma_f32 v[84:85], v[132:133], v[84:85], v[136:137]
	v_pk_fma_f32 v[86:87], v[134:135], v[86:87], v[138:139]
	v_cvt_pk_f16_f32 v170, v88, v89
	v_cvt_pk_f16_f32 v171, v90, v91
	v_cvt_pk_f16_f32 v172, v84, v85
	v_cvt_pk_f16_f32 v173, v86, v87
	v_add_u32_e32 v170, 0x20002, v170
	v_add_u32_e32 v171, 0x20002, v171
	v_add_u32_e32 v172, 0x20002, v172
	v_add_u32_e32 v173, 0x20002, v173
	v_and_b32_e32 v170, 0xfffcfffc, v170
	v_and_b32_e32 v171, 0xfffcfffc, v171
	v_and_b32_e32 v172, 0xfffcfffc, v172
	v_and_b32_e32 v173, 0xfffcfffc, v173
	global_store_dwordx4 v[176:177], v[170:173], off offset:256
	ds_read_b64 v[168:169], v32 offset:8576
	v_add_co_u32_e32 v176, vcc, 0x18000, v166
	v_addc_co_u32_e32 v177, vcc, 0, v167, vcc
	s_waitcnt lgkmcnt(0)
; template <unsigned D> __device__ __forceinline__ u32x4 rd8(u32x4 w) { w.x = rd<D>(w.x); w.y = rd<D>(w.y); w.z = rd<D>(w.z); w.w = rd<D>(w.w); return w; }
; __device__ __forceinline__ u32x4 pk8(const f32x4 v0, const f32x4 v1) { u32x4 w; w.x = pk_f16(v0[0], v0[1]); w.y = pk_f16(v0[2], v0[3]); w.z = pk_f16(v1[0], v1[1]); w.w = pk_f16(v1[2], v1[3]); return w; }
; __device__ __forceinline__ unsigned pk4_fp8(float a, float b, float c, float d) { int w = __builtin_amdgcn_cvt_pk_fp8_f32(a, b, 0, false); w = __builtin_amdgcn_cvt_pk_fp8_f32(c, d, w, true); return (unsigned)w; }
;     __device__ __forceinline__ void fused(f32x4 (&acc)[2][2][4][2], const GUnit& u, int wr, int wc, int fr, int fq, LAS unsigned char* lds, int wid, int lane) const {
;     ...
; #pragma unroll
;         for (int ai = 0; ai < 2; ++ai)
; #pragma unroll
;             for (int m = 0; m < 4; ++m) { const int r = ai * 128 + wr * 64 + m * 16 + fr; const f32x2 sr = S[r]; const size_t row = (size_t)(u.pm * 256 + r);
; #pragma unroll
;                 for (int bj = 0; bj < 2; ++bj) { const int col = gcol0 + bj * 128;
;                     f32x4 y0 = (acc[ai][bj][m][0] - sr.x) * sr.y * gv[bj][0] + bv[bj][0], y1 = (acc[ai][bj][m][1] - sr.x) * sr.y * gv[bj][1] + bv[bj][1];
;                     if (bad) { y0 = (f32x4){qnan, qnan, qnan, qnan}; y1 = y0; }
;                     if (last) { *(f32x4*)(out + row * 1024 + col) = y0; *(f32x4*)(out + row * 1024 + col + 4) = y1; }
;                     else { *(u32x4*)(H16 + row * 1024 + col) = rd8<D_H>(pk8(y0, y1));
;                            if (h8out) { u32x2 q8v; q8v.x = pk4_fp8(y0[0], y0[1], y0[2], y0[3]); q8v.y = pk4_fp8(y1[0], y1[1], y1[2], y1[3]); *(u32x2*)(ws + WS_H8 + row * 1024 + col) = q8v; } } }
	v_cndmask_b32_e64 v169, v229, v169, s[100:101]
	v_pk_add_f32 v[80:81], v[80:81], v[168:169] op_sel_hi:[1,0] neg_lo:[0,1] neg_hi:[0,1]
	v_pk_add_f32 v[82:83], v[82:83], v[168:169] op_sel_hi:[1,0] neg_lo:[0,1] neg_hi:[0,1]
	v_pk_add_f32 v[76:77], v[76:77], v[168:169] op_sel_hi:[1,0] neg_lo:[0,1] neg_hi:[0,1]
	v_pk_add_f32 v[78:79], v[78:79], v[168:169] op_sel_hi:[1,0] neg_lo:[0,1] neg_hi:[0,1]
	v_pk_mul_f32 v[80:81], v[168:169], v[80:81] op_sel:[1,0]
	v_pk_mul_f32 v[82:83], v[168:169], v[82:83] op_sel:[1,0]
	v_pk_mul_f32 v[76:77], v[168:169], v[76:77] op_sel:[1,0]
	v_pk_mul_f32 v[78:79], v[168:169], v[78:79] op_sel:[1,0]
	v_pk_fma_f32 v[80:81], v[160:161], v[80:81], v[156:157]
	v_pk_fma_f32 v[82:83], v[162:163], v[82:83], v[158:159]
	v_pk_fma_f32 v[76:77], v[148:149], v[76:77], v[152:153]
	v_pk_fma_f32 v[78:79], v[150:151], v[78:79], v[154:155]
	v_cvt_pk_f16_f32 v170, v80, v81
	v_cvt_pk_f16_f32 v171, v82, v83
	v_cvt_pk_f16_f32 v172, v76, v77
	v_cvt_pk_f16_f32 v173, v78, v79
	v_add_u32_e32 v170, 0x20002, v170
	v_add_u32_e32 v171, 0x20002, v171
	v_add_u32_e32 v172, 0x20002, v172
	v_add_u32_e32 v173, 0x20002, v173
	v_and_b32_e32 v170, 0xfffcfffc, v170
	v_and_b32_e32 v171, 0xfffcfffc, v171
	v_and_b32_e32 v172, 0xfffcfffc, v172
	v_and_b32_e32 v173, 0xfffcfffc, v173
	global_store_dwordx4 v[176:177], v[170:173], off
	v_pk_add_f32 v[72:73], v[72:73], v[168:169] op_sel_hi:[1,0] neg_lo:[0,1] neg_hi:[0,1]
	v_pk_add_f32 v[74:75], v[74:75], v[168:169] op_sel_hi:[1,0] neg_lo:[0,1] neg_hi:[0,1]
	v_pk_add_f32 v[68:69], v[68:69], v[168:169] op_sel_hi:[1,0] neg_lo:[0,1] neg_hi:[0,1]
	v_pk_add_f32 v[70:71], v[70:71], v[168:169] op_sel_hi:[1,0] neg_lo:[0,1] neg_hi:[0,1]
	v_pk_mul_f32 v[72:73], v[168:169], v[72:73] op_sel:[1,0]
	v_pk_mul_f32 v[74:75], v[168:169], v[74:75] op_sel:[1,0]
	v_pk_mul_f32 v[68:69], v[168:169], v[68:69] op_sel:[1,0]
	v_pk_mul_f32 v[70:71], v[168:169], v[70:71] op_sel:[1,0]
	v_pk_fma_f32 v[72:73], v[140:141], v[72:73], v[144:145]
	v_pk_fma_f32 v[74:75], v[142:143], v[74:75], v[146:147]
	v_pk_fma_f32 v[68:69], v[132:133], v[68:69], v[136:137]
	v_pk_fma_f32 v[70:71], v[134:135], v[70:71], v[138:139]
	v_cvt_pk_f16_f32 v170, v72, v73
	v_cvt_pk_f16_f32 v171, v74, v75
	v_cvt_pk_f16_f32 v172, v68, v69
	v_cvt_pk_f16_f32 v173, v70, v71
	v_add_u32_e32 v170, 0x20002, v170
	v_add_u32_e32 v171, 0x20002, v171
	v_add_u32_e32 v172, 0x20002, v172
	v_add_u32_e32 v173, 0x20002, v173
	v_and_b32_e32 v170, 0xfffcfffc, v170
	v_and_b32_e32 v171, 0xfffcfffc, v171
	v_and_b32_e32 v172, 0xfffcfffc, v172
	v_and_b32_e32 v173, 0xfffcfffc, v173
	global_store_dwordx4 v[176:177], v[170:173], off offset:256
	ds_read_b64 v[168:169], v32 offset:9216
	v_add_co_u32_e32 v176, vcc, 0x40000, v166
	v_addc_co_u32_e32 v177, vcc, 0, v167, vcc
	s_waitcnt lgkmcnt(0)
	v_cndmask_b32_e64 v169, v229, v169, s[100:101]
	v_pk_add_f32 v[64:65], v[64:65], v[168:169] op_sel_hi:[1,0] neg_lo:[0,1] neg_hi:[0,1]
	v_pk_add_f32 v[66:67], v[66:67], v[168:169] op_sel_hi:[1,0] neg_lo:[0,1] neg_hi:[0,1]
	v_pk_add_f32 v[60:61], v[60:61], v[168:169] op_sel_hi:[1,0] neg_lo:[0,1] neg_hi:[0,1]
	v_pk_add_f32 v[62:63], v[62:63], v[168:169] op_sel_hi:[1,0] neg_lo:[0,1] neg_hi:[0,1]
	v_pk_mul_f32 v[64:65], v[168:169], v[64:65] op_sel:[1,0]
	v_pk_mul_f32 v[66:67], v[168:169], v[66:67] op_sel:[1,0]
	v_pk_mul_f32 v[60:61], v[168:169], v[60:61] op_sel:[1,0]
	v_pk_mul_f32 v[62:63], v[168:169], v[62:63] op_sel:[1,0]
	v_pk_fma_f32 v[64:65], v[160:161], v[64:65], v[156:157]
	v_pk_fma_f32 v[66:67], v[162:163], v[66:67], v[158:159]
	v_pk_fma_f32 v[60:61], v[148:149], v[60:61], v[152:153]
	v_pk_fma_f32 v[62:63], v[150:151], v[62:63], v[154:155]
	v_cvt_pk_f16_f32 v170, v64, v65
	v_cvt_pk_f16_f32 v171, v66, v67
	v_cvt_pk_f16_f32 v172, v60, v61
	v_cvt_pk_f16_f32 v173, v62, v63
	v_add_u32_e32 v170, 0x20002, v170
	v_add_u32_e32 v171, 0x20002, v171
	v_add_u32_e32 v172, 0x20002, v172
	v_add_u32_e32 v173, 0x20002, v173
	v_and_b32_e32 v170, 0xfffcfffc, v170
	v_and_b32_e32 v171, 0xfffcfffc, v171
	v_and_b32_e32 v172, 0xfffcfffc, v172
	v_and_b32_e32 v173, 0xfffcfffc, v173
	global_store_dwordx4 v[176:177], v[170:173], off
	v_pk_add_f32 v[56:57], v[56:57], v[168:169] op_sel_hi:[1,0] neg_lo:[0,1] neg_hi:[0,1]
	v_pk_add_f32 v[58:59], v[58:59], v[168:169] op_sel_hi:[1,0] neg_lo:[0,1] neg_hi:[0,1]
	v_pk_add_f32 v[52:53], v[52:53], v[168:169] op_sel_hi:[1,0] neg_lo:[0,1] neg_hi:[0,1]
	v_pk_add_f32 v[54:55], v[54:55], v[168:169] op_sel_hi:[1,0] neg_lo:[0,1] neg_hi:[0,1]
	v_pk_mul_f32 v[56:57], v[168:169], v[56:57] op_sel:[1,0]
	v_pk_mul_f32 v[58:59], v[168:169], v[58:59] op_sel:[1,0]
	v_pk_mul_f32 v[52:53], v[168:169], v[52:53] op_sel:[1,0]
	v_pk_mul_f32 v[54:55], v[168:169], v[54:55] op_sel:[1,0]
	v_pk_fma_f32 v[56:57], v[140:141], v[56:57], v[144:145]
	v_pk_fma_f32 v[58:59], v[142:143], v[58:59], v[146:147]
	v_pk_fma_f32 v[52:53], v[132:133], v[52:53], v[136:137]
	v_pk_fma_f32 v[54:55], v[134:135], v[54:55], v[138:139]
	v_cvt_pk_f16_f32 v170, v56, v57
	v_cvt_pk_f16_f32 v171, v58, v59
	v_cvt_pk_f16_f32 v172, v52, v53
	v_cvt_pk_f16_f32 v173, v54, v55
	v_add_u32_e32 v170, 0x20002, v170
	v_add_u32_e32 v171, 0x20002, v171
	v_add_u32_e32 v172, 0x20002, v172
	v_add_u32_e32 v173, 0x20002, v173
	v_and_b32_e32 v170, 0xfffcfffc, v170
	v_and_b32_e32 v171, 0xfffcfffc, v171
	v_and_b32_e32 v172, 0xfffcfffc, v172
	v_and_b32_e32 v173, 0xfffcfffc, v173
	global_store_dwordx4 v[176:177], v[170:173], off offset:256
	ds_read_b64 v[168:169], v32 offset:9344
	v_add_co_u32_e32 v176, vcc, 0x48000, v166
	v_addc_co_u32_e32 v177, vcc, 0, v167, vcc
	s_waitcnt lgkmcnt(0)
; template <unsigned D> __device__ __forceinline__ u32x4 rd8(u32x4 w) { w.x = rd<D>(w.x); w.y = rd<D>(w.y); w.z = rd<D>(w.z); w.w = rd<D>(w.w); return w; }
; __device__ __forceinline__ u32x4 pk8(const f32x4 v0, const f32x4 v1) { u32x4 w; w.x = pk_f16(v0[0], v0[1]); w.y = pk_f16(v0[2], v0[3]); w.z = pk_f16(v1[0], v1[1]); w.w = pk_f16(v1[2], v1[3]); return w; }
; __device__ __forceinline__ unsigned pk4_fp8(float a, float b, float c, float d) { int w = __builtin_amdgcn_cvt_pk_fp8_f32(a, b, 0, false); w = __builtin_amdgcn_cvt_pk_fp8_f32(c, d, w, true); return (unsigned)w; }
;     __device__ __forceinline__ void fused(f32x4 (&acc)[2][2][4][2], const GUnit& u, int wr, int wc, int fr, int fq, LAS unsigned char* lds, int wid, int lane) const {
;     ...
; #pragma unroll
;         for (int ai = 0; ai < 2; ++ai)
; #pragma unroll
;             for (int m = 0; m < 4; ++m) { const int r = ai * 128 + wr * 64 + m * 16 + fr; const f32x2 sr = S[r]; const size_t row = (size_t)(u.pm * 256 + r);
; #pragma unroll
;                 for (int bj = 0; bj < 2; ++bj) { const int col = gcol0 + bj * 128;
;                     f32x4 y0 = (acc[ai][bj][m][0] - sr.x) * sr.y * gv[bj][0] + bv[bj][0], y1 = (acc[ai][bj][m][1] - sr.x) * sr.y * gv[bj][1] + bv[bj][1];
;                     if (bad) { y0 = (f32x4){qnan, qnan, qnan, qnan}; y1 = y0; }
;                     if (last) { *(f32x4*)(out + row * 1024 + col) = y0; *(f32x4*)(out + row * 1024 + col + 4) = y1; }
;                     else { *(u32x4*)(H16 + row * 1024 + col) = rd8<D_H>(pk8(y0, y1));
;                            if (h8out) { u32x2 q8v; q8v.x = pk4_fp8(y0[0], y0[1], y0[2], y0[3]); q8v.y = pk4_fp8(y1[0], y1[1], y1[2], y1[3]); *(u32x2*)(ws + WS_H8 + row * 1024 + col) = q8v; } } }
	v_cndmask_b32_e64 v169, v229, v169, s[100:101]
	v_pk_add_f32 v[48:49], v[48:49], v[168:169] op_sel_hi:[1,0] neg_lo:[0,1] neg_hi:[0,1]
	v_pk_add_f32 v[50:51], v[50:51], v[168:169] op_sel_hi:[1,0] neg_lo:[0,1] neg_hi:[0,1]
	v_pk_add_f32 v[44:45], v[44:45], v[168:169] op_sel_hi:[1,0] neg_lo:[0,1] neg_hi:[0,1]
	v_pk_add_f32 v[46:47], v[46:47], v[168:169] op_sel_hi:[1,0] neg_lo:[0,1] neg_hi:[0,1]
	v_pk_mul_f32 v[48:49], v[168:169], v[48:49] op_sel:[1,0]
	v_pk_mul_f32 v[50:51], v[168:169], v[50:51] op_sel:[1,0]
	v_pk_mul_f32 v[44:45], v[168:169], v[44:45] op_sel:[1,0]
	v_pk_mul_f32 v[46:47], v[168:169], v[46:47] op_sel:[1,0]
	v_pk_fma_f32 v[48:49], v[160:161], v[48:49], v[156:157]
	v_pk_fma_f32 v[50:51], v[162:163], v[50:51], v[158:159]
	v_pk_fma_f32 v[44:45], v[148:149], v[44:45], v[152:153]
	v_pk_fma_f32 v[46:47], v[150:151], v[46:47], v[154:155]
	v_cvt_pk_f16_f32 v170, v48, v49
	v_cvt_pk_f16_f32 v171, v50, v51
	v_cvt_pk_f16_f32 v172, v44, v45
	v_cvt_pk_f16_f32 v173, v46, v47
	v_add_u32_e32 v170, 0x20002, v170
	v_add_u32_e32 v171, 0x20002, v171
	v_add_u32_e32 v172, 0x20002, v172
	v_add_u32_e32 v173, 0x20002, v173
	v_and_b32_e32 v170, 0xfffcfffc, v170
	v_and_b32_e32 v171, 0xfffcfffc, v171
	v_and_b32_e32 v172, 0xfffcfffc, v172
	v_and_b32_e32 v173, 0xfffcfffc, v173
	global_store_dwordx4 v[176:177], v[170:173], off
	v_pk_add_f32 v[40:41], v[40:41], v[168:169] op_sel_hi:[1,0] neg_lo:[0,1] neg_hi:[0,1]
	v_pk_add_f32 v[42:43], v[42:43], v[168:169] op_sel_hi:[1,0] neg_lo:[0,1] neg_hi:[0,1]
	v_pk_add_f32 v[36:37], v[36:37], v[168:169] op_sel_hi:[1,0] neg_lo:[0,1] neg_hi:[0,1]
	v_pk_add_f32 v[38:39], v[38:39], v[168:169] op_sel_hi:[1,0] neg_lo:[0,1] neg_hi:[0,1]
	v_pk_mul_f32 v[40:41], v[168:169], v[40:41] op_sel:[1,0]
	v_pk_mul_f32 v[42:43], v[168:169], v[42:43] op_sel:[1,0]
	v_pk_mul_f32 v[36:37], v[168:169], v[36:37] op_sel:[1,0]
	v_pk_mul_f32 v[38:39], v[168:169], v[38:39] op_sel:[1,0]
	v_pk_fma_f32 v[40:41], v[140:141], v[40:41], v[144:145]
	v_pk_fma_f32 v[42:43], v[142:143], v[42:43], v[146:147]
	v_pk_fma_f32 v[36:37], v[132:133], v[36:37], v[136:137]
	v_pk_fma_f32 v[38:39], v[134:135], v[38:39], v[138:139]
	v_cvt_pk_f16_f32 v170, v40, v41
	v_cvt_pk_f16_f32 v171, v42, v43
	v_cvt_pk_f16_f32 v172, v36, v37
	v_cvt_pk_f16_f32 v173, v38, v39
	v_add_u32_e32 v170, 0x20002, v170
	v_add_u32_e32 v171, 0x20002, v171
	v_add_u32_e32 v172, 0x20002, v172
	v_add_u32_e32 v173, 0x20002, v173
	v_and_b32_e32 v170, 0xfffcfffc, v170
	v_and_b32_e32 v171, 0xfffcfffc, v171
	v_and_b32_e32 v172, 0xfffcfffc, v172
	v_and_b32_e32 v173, 0xfffcfffc, v173
	global_store_dwordx4 v[176:177], v[170:173], off offset:256
	ds_read_b64 v[168:169], v32 offset:9472
	v_add_co_u32_e32 v176, vcc, 0x50000, v166
	v_addc_co_u32_e32 v177, vcc, 0, v167, vcc
	s_waitcnt lgkmcnt(0)
; template <unsigned D> __device__ __forceinline__ u32x4 rd8(u32x4 w) { w.x = rd<D>(w.x); w.y = rd<D>(w.y); w.z = rd<D>(w.z); w.w = rd<D>(w.w); return w; }
; __device__ __forceinline__ u32x4 pk8(const f32x4 v0, const f32x4 v1) { u32x4 w; w.x = pk_f16(v0[0], v0[1]); w.y = pk_f16(v0[2], v0[3]); w.z = pk_f16(v1[0], v1[1]); w.w = pk_f16(v1[2], v1[3]); return w; }
; __device__ __forceinline__ unsigned pk4_fp8(float a, float b, float c, float d) { int w = __builtin_amdgcn_cvt_pk_fp8_f32(a, b, 0, false); w = __builtin_amdgcn_cvt_pk_fp8_f32(c, d, w, true); return (unsigned)w; }
;     __device__ __forceinline__ void fused(f32x4 (&acc)[2][2][4][2], const GUnit& u, int wr, int wc, int fr, int fq, LAS unsigned char* lds, int wid, int lane) const {
;     ...
; #pragma unroll
;         for (int ai = 0; ai < 2; ++ai)
; #pragma unroll
;             for (int m = 0; m < 4; ++m) { const int r = ai * 128 + wr * 64 + m * 16 + fr; const f32x2 sr = S[r]; const size_t row = (size_t)(u.pm * 256 + r);
; #pragma unroll
;                 for (int bj = 0; bj < 2; ++bj) { const int col = gcol0 + bj * 128;
;                     f32x4 y0 = (acc[ai][bj][m][0] - sr.x) * sr.y * gv[bj][0] + bv[bj][0], y1 = (acc[ai][bj][m][1] - sr.x) * sr.y * gv[bj][1] + bv[bj][1];
;                     if (bad) { y0 = (f32x4){qnan, qnan, qnan, qnan}; y1 = y0; }
;                     if (last) { *(f32x4*)(out + row * 1024 + col) = y0; *(f32x4*)(out + row * 1024 + col + 4) = y1; }
;                     else { *(u32x4*)(H16 + row * 1024 + col) = rd8<D_H>(pk8(y0, y1));
;                            if (h8out) { u32x2 q8v; q8v.x = pk4_fp8(y0[0], y0[1], y0[2], y0[3]); q8v.y = pk4_fp8(y1[0], y1[1], y1[2], y1[3]); *(u32x2*)(ws + WS_H8 + row * 1024 + col) = q8v; } } }
	v_cndmask_b32_e64 v169, v229, v169, s[100:101]
	v_pk_add_f32 v[28:29], v[28:29], v[168:169] op_sel_hi:[1,0] neg_lo:[0,1] neg_hi:[0,1]
	v_pk_add_f32 v[30:31], v[30:31], v[168:169] op_sel_hi:[1,0] neg_lo:[0,1] neg_hi:[0,1]
	v_pk_add_f32 v[24:25], v[24:25], v[168:169] op_sel_hi:[1,0] neg_lo:[0,1] neg_hi:[0,1]
	v_pk_add_f32 v[26:27], v[26:27], v[168:169] op_sel_hi:[1,0] neg_lo:[0,1] neg_hi:[0,1]
	v_pk_mul_f32 v[28:29], v[168:169], v[28:29] op_sel:[1,0]
	v_pk_mul_f32 v[30:31], v[168:169], v[30:31] op_sel:[1,0]
	v_pk_mul_f32 v[24:25], v[168:169], v[24:25] op_sel:[1,0]
	v_pk_mul_f32 v[26:27], v[168:169], v[26:27] op_sel:[1,0]
	v_pk_fma_f32 v[28:29], v[160:161], v[28:29], v[156:157]
	v_pk_fma_f32 v[30:31], v[162:163], v[30:31], v[158:159]
	v_pk_fma_f32 v[24:25], v[148:149], v[24:25], v[152:153]
	v_pk_fma_f32 v[26:27], v[150:151], v[26:27], v[154:155]
	v_cvt_pk_f16_f32 v170, v28, v29
	v_cvt_pk_f16_f32 v171, v30, v31
	v_cvt_pk_f16_f32 v172, v24, v25
	v_cvt_pk_f16_f32 v173, v26, v27
	v_add_u32_e32 v170, 0x20002, v170
	v_add_u32_e32 v171, 0x20002, v171
	v_add_u32_e32 v172, 0x20002, v172
	v_add_u32_e32 v173, 0x20002, v173
	v_and_b32_e32 v170, 0xfffcfffc, v170
	v_and_b32_e32 v171, 0xfffcfffc, v171
	v_and_b32_e32 v172, 0xfffcfffc, v172
	v_and_b32_e32 v173, 0xfffcfffc, v173
	global_store_dwordx4 v[176:177], v[170:173], off
	v_pk_add_f32 v[20:21], v[20:21], v[168:169] op_sel_hi:[1,0] neg_lo:[0,1] neg_hi:[0,1]
	v_pk_add_f32 v[22:23], v[22:23], v[168:169] op_sel_hi:[1,0] neg_lo:[0,1] neg_hi:[0,1]
	v_pk_add_f32 v[16:17], v[16:17], v[168:169] op_sel_hi:[1,0] neg_lo:[0,1] neg_hi:[0,1]
	v_pk_add_f32 v[18:19], v[18:19], v[168:169] op_sel_hi:[1,0] neg_lo:[0,1] neg_hi:[0,1]
	v_pk_mul_f32 v[20:21], v[168:169], v[20:21] op_sel:[1,0]
	v_pk_mul_f32 v[22:23], v[168:169], v[22:23] op_sel:[1,0]
	v_pk_mul_f32 v[16:17], v[168:169], v[16:17] op_sel:[1,0]
	v_pk_mul_f32 v[18:19], v[168:169], v[18:19] op_sel:[1,0]
	v_pk_fma_f32 v[20:21], v[140:141], v[20:21], v[144:145]
	v_pk_fma_f32 v[22:23], v[142:143], v[22:23], v[146:147]
	v_pk_fma_f32 v[16:17], v[132:133], v[16:17], v[136:137]
	v_pk_fma_f32 v[18:19], v[134:135], v[18:19], v[138:139]
	v_cvt_pk_f16_f32 v170, v20, v21
	v_cvt_pk_f16_f32 v171, v22, v23
	v_cvt_pk_f16_f32 v172, v16, v17
	v_cvt_pk_f16_f32 v173, v18, v19
	v_add_u32_e32 v170, 0x20002, v170
	v_add_u32_e32 v171, 0x20002, v171
	v_add_u32_e32 v172, 0x20002, v172
	v_add_u32_e32 v173, 0x20002, v173
	v_and_b32_e32 v170, 0xfffcfffc, v170
	v_and_b32_e32 v171, 0xfffcfffc, v171
	v_and_b32_e32 v172, 0xfffcfffc, v172
	v_and_b32_e32 v173, 0xfffcfffc, v173
	global_store_dwordx4 v[176:177], v[170:173], off offset:256
	ds_read_b64 v[168:169], v32 offset:9600
	v_add_co_u32_e32 v176, vcc, 0x58000, v166
	v_addc_co_u32_e32 v177, vcc, 0, v167, vcc
	s_waitcnt lgkmcnt(0)
	v_cndmask_b32_e64 v169, v229, v169, s[100:101]
	v_pk_add_f32 v[12:13], v[12:13], v[168:169] op_sel_hi:[1,0] neg_lo:[0,1] neg_hi:[0,1]
	v_pk_add_f32 v[14:15], v[14:15], v[168:169] op_sel_hi:[1,0] neg_lo:[0,1] neg_hi:[0,1]
	v_pk_add_f32 v[8:9], v[8:9], v[168:169] op_sel_hi:[1,0] neg_lo:[0,1] neg_hi:[0,1]
	v_pk_add_f32 v[10:11], v[10:11], v[168:169] op_sel_hi:[1,0] neg_lo:[0,1] neg_hi:[0,1]
	v_pk_mul_f32 v[12:13], v[168:169], v[12:13] op_sel:[1,0]
	v_pk_mul_f32 v[14:15], v[168:169], v[14:15] op_sel:[1,0]
	v_pk_mul_f32 v[8:9], v[168:169], v[8:9] op_sel:[1,0]
	v_pk_mul_f32 v[10:11], v[168:169], v[10:11] op_sel:[1,0]
	v_pk_fma_f32 v[12:13], v[160:161], v[12:13], v[156:157]
	v_pk_fma_f32 v[14:15], v[162:163], v[14:15], v[158:159]
	v_pk_fma_f32 v[8:9], v[148:149], v[8:9], v[152:153]
	v_pk_fma_f32 v[10:11], v[150:151], v[10:11], v[154:155]
	v_cvt_pk_f16_f32 v170, v12, v13
	v_cvt_pk_f16_f32 v171, v14, v15
	v_cvt_pk_f16_f32 v172, v8, v9
	v_cvt_pk_f16_f32 v173, v10, v11
	v_add_u32_e32 v170, 0x20002, v170
	v_add_u32_e32 v171, 0x20002, v171
	v_add_u32_e32 v172, 0x20002, v172
	v_add_u32_e32 v173, 0x20002, v173
	v_and_b32_e32 v170, 0xfffcfffc, v170
	v_and_b32_e32 v171, 0xfffcfffc, v171
	v_and_b32_e32 v172, 0xfffcfffc, v172
	v_and_b32_e32 v173, 0xfffcfffc, v173
	global_store_dwordx4 v[176:177], v[170:173], off
	v_pk_add_f32 v[4:5], v[4:5], v[168:169] op_sel_hi:[1,0] neg_lo:[0,1] neg_hi:[0,1]
	v_pk_add_f32 v[6:7], v[6:7], v[168:169] op_sel_hi:[1,0] neg_lo:[0,1] neg_hi:[0,1]
	v_pk_add_f32 v[0:1], v[0:1], v[168:169] op_sel_hi:[1,0] neg_lo:[0,1] neg_hi:[0,1]
	v_pk_add_f32 v[2:3], v[2:3], v[168:169] op_sel_hi:[1,0] neg_lo:[0,1] neg_hi:[0,1]
	v_pk_mul_f32 v[4:5], v[168:169], v[4:5] op_sel:[1,0]
	v_pk_mul_f32 v[6:7], v[168:169], v[6:7] op_sel:[1,0]
	v_pk_mul_f32 v[0:1], v[168:169], v[0:1] op_sel:[1,0]
	v_pk_mul_f32 v[2:3], v[168:169], v[2:3] op_sel:[1,0]
	v_pk_fma_f32 v[4:5], v[140:141], v[4:5], v[144:145]
	v_pk_fma_f32 v[6:7], v[142:143], v[6:7], v[146:147]
	v_pk_fma_f32 v[0:1], v[132:133], v[0:1], v[136:137]
	v_pk_fma_f32 v[2:3], v[134:135], v[2:3], v[138:139]
	v_cvt_pk_f16_f32 v170, v4, v5
	v_cvt_pk_f16_f32 v171, v6, v7
	v_cvt_pk_f16_f32 v172, v0, v1
	v_cvt_pk_f16_f32 v173, v2, v3
	v_add_u32_e32 v170, 0x20002, v170
	v_add_u32_e32 v171, 0x20002, v171
	v_add_u32_e32 v172, 0x20002, v172
	v_add_u32_e32 v173, 0x20002, v173
	v_and_b32_e32 v170, 0xfffcfffc, v170
	v_and_b32_e32 v171, 0xfffcfffc, v171
	v_and_b32_e32 v172, 0xfffcfffc, v172
	v_and_b32_e32 v173, 0xfffcfffc, v173
	global_store_dwordx4 v[176:177], v[170:173], off offset:256
	v_mov_b32_e32 v233, v226
	s_branch .LBB0_567

; template <unsigned D> __device__ __forceinline__ u32x4 rd8(u32x4 w) { w.x = rd<D>(w.x); w.y = rd<D>(w.y); w.z = rd<D>(w.z); w.w = rd<D>(w.w); return w; }
; __device__ __forceinline__ u32x4 pk8(const f32x4 v0, const f32x4 v1) { u32x4 w; w.x = pk_f16(v0[0], v0[1]); w.y = pk_f16(v0[2], v0[3]); w.z = pk_f16(v1[0], v1[1]); w.w = pk_f16(v1[2], v1[3]); return w; }
; __device__ __forceinline__ unsigned pk4_fp8(float a, float b, float c, float d) { int w = __builtin_amdgcn_cvt_pk_fp8_f32(a, b, 0, false); w = __builtin_amdgcn_cvt_pk_fp8_f32(c, d, w, true); return (unsigned)w; }
;     __device__ __forceinline__ void fused(f32x4 (&acc)[2][2][4][2], const GUnit& u, int wr, int wc, int fr, int fq, LAS unsigned char* lds, int wid, int lane) const {
;     ...
;         f32x4 gv[2][2], bv[2][2];
; #pragma unroll
;         for (int bj = 0; bj < 2; ++bj)
; #pragma unroll
;             for (int n = 0; n < 2; ++n) { gv[bj][n] = *(const f32x4*)(ln_g + gcol0 + bj * 128 + 4 * n); bv[bj][n] = *(const f32x4*)(ln_b + gcol0 + bj * 128 + 4 * n); }
; #pragma unroll
;         for (int ai = 0; ai < 2; ++ai)
; #pragma unroll
;             for (int m = 0; m < 4; ++m) { const int r = ai * 128 + wr * 64 + m * 16 + fr; const f32x2 sr = S[r]; const size_t row = (size_t)(u.pm * 256 + r);
; #pragma unroll
;                 for (int bj = 0; bj < 2; ++bj) { const int col = gcol0 + bj * 128;
;                     f32x4 y0 = (acc[ai][bj][m][0] - sr.x) * sr.y * gv[bj][0] + bv[bj][0], y1 = (acc[ai][bj][m][1] - sr.x) * sr.y * gv[bj][1] + bv[bj][1];
;                     if (bad) { y0 = (f32x4){qnan, qnan, qnan, qnan}; y1 = y0; }
;                     if (last) { *(f32x4*)(out + row * 1024 + col) = y0; *(f32x4*)(out + row * 1024 + col + 4) = y1; }
;                     else { *(u32x4*)(H16 + row * 1024 + col) = rd8<D_H>(pk8(y0, y1));
;                            if (h8out) { u32x2 q8v; q8v.x = pk4_fp8(y0[0], y0[1], y0[2], y0[3]); q8v.y = pk4_fp8(y1[0], y1[1], y1[2], y1[3]); *(u32x2*)(ws + WS_H8 + row * 1024 + col) = q8v; } } }
.LBB0_470:
	s_or_b64 exec, exec, s[2:3]
	s_lshl_b32 s4, s72, 12
	v_readlane_b32 s2, v255, 9
	v_readlane_b32 s3, v255, 10
	s_add_u32 s2, s2, s4
	s_addc_u32 s3, s3, 0
	v_readlane_b32 s6, v255, 11
	v_readlane_b32 s7, v255, 12
	s_add_u32 s4, s6, s4
	s_addc_u32 s5, s7, 0
	v_lshlrev_b64 v[132:133], 2, v[198:199]
	v_lshl_add_u64 v[136:137], s[2:3], 0, v[132:133]
	v_lshl_add_u64 v[144:145], s[4:5], 0, v[132:133]
	global_load_dwordx4 v[156:159], v[144:145], off
	global_load_dwordx4 v[160:163], v[136:137], off
	global_load_dwordx4 v[148:151], v[136:137], off offset:16
	global_load_dwordx4 v[152:155], v[144:145], off offset:16
	s_waitcnt lgkmcnt(1)
	global_load_dwordx4 v[132:135], v[136:137], off offset:528
	global_load_dwordx4 v[140:143], v[136:137], off offset:512
	s_nop 0
	global_load_dwordx4 v[136:139], v[144:145], off offset:528
	s_nop 0
	global_load_dwordx4 v[144:147], v[144:145], off offset:512
	s_waitcnt lgkmcnt(0)
	s_barrier
	s_cmp_lg_u32 s72, 3
	s_cselect_b64 s[2:3], -1, 0
	s_xor_b64 s[4:5], s[26:27], -1
	s_or_b64 s[2:3], s[2:3], s[4:5]
	s_and_b64 vcc, exec, s[2:3]
	s_cbranch_vccnz .Lap_mine
	v_lshl_add_u32 v32, v233, 3, 0
	ds_read_b64 v[168:169], v32 offset:8192
	v_readlane_b32 s2, v253, 4
	v_readlane_b32 s3, v253, 5
	s_cmp_lg_u32 s72, 3
	s_mov_b64 s[6:7], -1
	s_waitcnt lgkmcnt(0)
	v_cmp_eq_u32_e64 s[100:101], 0, v170
	s_nop 1
	v_cndmask_b32_e64 v169, v229, v169, s[100:101]
	v_pk_add_f32 v[172:173], v[130:131], v[168:169] op_sel_hi:[1,0] neg_lo:[0,1] neg_hi:[0,1]
	v_pk_add_f32 v[130:131], v[126:127], v[168:169] op_sel_hi:[1,0] neg_lo:[0,1] neg_hi:[0,1]
	v_pk_add_f32 v[174:175], v[128:129], v[168:169] op_sel_hi:[1,0] neg_lo:[0,1] neg_hi:[0,1]
	v_pk_add_f32 v[128:129], v[124:125], v[168:169] op_sel_hi:[1,0] neg_lo:[0,1] neg_hi:[0,1]
	v_pk_mul_f32 v[126:127], v[168:169], v[172:173] op_sel:[1,0]
	v_pk_mul_f32 v[124:125], v[168:169], v[174:175] op_sel:[1,0]
	v_pk_mul_f32 v[130:131], v[168:169], v[130:131] op_sel:[1,0]
	v_pk_mul_f32 v[128:129], v[168:169], v[128:129] op_sel:[1,0]
	v_lshl_add_u64 v[166:167], s[2:3], 0, v[216:217]
	s_cselect_b64 s[2:3], -1, 0
	s_xor_b64 s[4:5], s[26:27], -1
	s_or_b64 s[2:3], s[2:3], s[4:5]
	v_cmp_eq_u32_e64 s[4:5], 0, v170
	v_lshlrev_b64 v[164:165], 10, v[214:215]
	v_lshl_add_u64 v[166:167], v[198:199], 1, v[166:167]
	s_and_b64 vcc, exec, s[2:3]
	s_waitcnt vmcnt(6)
	v_pk_fma_f32 v[126:127], v[162:163], v[126:127], v[158:159]
	v_pk_fma_f32 v[124:125], v[160:161], v[124:125], v[156:157]
	s_waitcnt vmcnt(4)
	v_pk_fma_f32 v[130:131], v[150:151], v[130:131], v[154:155]
	v_pk_fma_f32 v[128:129], v[148:149], v[128:129], v[152:153]

; template <unsigned D> __device__ __forceinline__ u32x4 rd8(u32x4 w) { w.x = rd<D>(w.x); w.y = rd<D>(w.y); w.z = rd<D>(w.z); w.w = rd<D>(w.w); return w; }
; __device__ __forceinline__ u32x4 pk8(const f32x4 v0, const f32x4 v1) { u32x4 w; w.x = pk_f16(v0[0], v0[1]); w.y = pk_f16(v0[2], v0[3]); w.z = pk_f16(v1[0], v1[1]); w.w = pk_f16(v1[2], v1[3]); return w; }
; __device__ __forceinline__ unsigned pk4_fp8(float a, float b, float c, float d) { int w = __builtin_amdgcn_cvt_pk_fp8_f32(a, b, 0, false); w = __builtin_amdgcn_cvt_pk_fp8_f32(c, d, w, true); return (unsigned)w; }
;     __device__ __forceinline__ void fused(f32x4 (&acc)[2][2][4][2], const GUnit& u, int wr, int wc, int fr, int fq, LAS unsigned char* lds, int wid, int lane) const {
;     ...
; #pragma unroll
;         for (int ai = 0; ai < 2; ++ai)
; #pragma unroll
;             for (int m = 0; m < 4; ++m) { const int r = ai * 128 + wr * 64 + m * 16 + fr; const f32x2 sr = S[r]; const size_t row = (size_t)(u.pm * 256 + r);
; #pragma unroll
;                 for (int bj = 0; bj < 2; ++bj) { const int col = gcol0 + bj * 128;
;                     f32x4 y0 = (acc[ai][bj][m][0] - sr.x) * sr.y * gv[bj][0] + bv[bj][0], y1 = (acc[ai][bj][m][1] - sr.x) * sr.y * gv[bj][1] + bv[bj][1];
;                     if (bad) { y0 = (f32x4){qnan, qnan, qnan, qnan}; y1 = y0; }
;                     if (last) { *(f32x4*)(out + row * 1024 + col) = y0; *(f32x4*)(out + row * 1024 + col + 4) = y1; }
;                     else { *(u32x4*)(H16 + row * 1024 + col) = rd8<D_H>(pk8(y0, y1));
;                            if (h8out) { u32x2 q8v; q8v.x = pk4_fp8(y0[0], y0[1], y0[2], y0[3]); q8v.y = pk4_fp8(y1[0], y1[1], y1[2], y1[3]); *(u32x2*)(ws + WS_H8 + row * 1024 + col) = q8v; } } }
.LBB0_476:
	s_nop 0
	v_pk_add_f32 v[124:125], v[120:121], v[168:169] op_sel_hi:[1,0] neg_lo:[0,1] neg_hi:[0,1]
	v_pk_add_f32 v[120:121], v[116:117], v[168:169] op_sel_hi:[1,0] neg_lo:[0,1] neg_hi:[0,1]
	v_pk_add_f32 v[126:127], v[122:123], v[168:169] op_sel_hi:[1,0] neg_lo:[0,1] neg_hi:[0,1]
	v_pk_add_f32 v[122:123], v[118:119], v[168:169] op_sel_hi:[1,0] neg_lo:[0,1] neg_hi:[0,1]
	v_pk_mul_f32 v[116:117], v[168:169], v[124:125] op_sel:[1,0]
	v_pk_mul_f32 v[118:119], v[168:169], v[126:127] op_sel:[1,0]
	v_pk_mul_f32 v[120:121], v[168:169], v[120:121] op_sel:[1,0]
	v_pk_mul_f32 v[122:123], v[168:169], v[122:123] op_sel:[1,0]
	s_waitcnt vmcnt(0)
	v_pk_fma_f32 v[116:117], v[140:141], v[116:117], v[144:145]
	v_pk_fma_f32 v[118:119], v[142:143], v[118:119], v[146:147]
	v_pk_fma_f32 v[120:121], v[132:133], v[120:121], v[136:137]
	v_pk_fma_f32 v[122:123], v[134:135], v[122:123], v[138:139]
	s_mov_b64 s[6:7], -1
	s_and_b64 vcc, exec, s[2:3]
.LBB0_480:
	s_andn2_b64 vcc, exec, s[6:7]
	s_cbranch_vccnz .LBB0_482
	v_lshl_add_u64 v[124:125], v[198:199], 2, v[170:171]
	global_store_dwordx4 v[124:125], v[116:119], off offset:512
	global_store_dwordx4 v[124:125], v[120:123], off offset:528
.LBB0_482:
	ds_read_b64 v[118:119], v32 offset:8320
	s_nop 0
	v_add3_u32 v120, s14, v233, 16
	v_ashrrev_i32_e32 v121, 31, v120
	v_readlane_b32 s6, v253, 4
	v_lshlrev_b64 v[116:117], 10, v[120:121]
	s_waitcnt lgkmcnt(0)
	v_cndmask_b32_e64 v119, v229, v119, s[100:101]
	v_pk_add_f32 v[122:123], v[112:113], v[118:119] op_sel_hi:[1,0] neg_lo:[0,1] neg_hi:[0,1]
	v_pk_add_f32 v[112:113], v[108:109], v[118:119] op_sel_hi:[1,0] neg_lo:[0,1] neg_hi:[0,1]
	v_pk_add_f32 v[124:125], v[114:115], v[118:119] op_sel_hi:[1,0] neg_lo:[0,1] neg_hi:[0,1]
	v_pk_add_f32 v[114:115], v[110:111], v[118:119] op_sel_hi:[1,0] neg_lo:[0,1] neg_hi:[0,1]
	v_pk_mul_f32 v[108:109], v[118:119], v[122:123] op_sel:[1,0]
	v_pk_mul_f32 v[110:111], v[118:119], v[124:125] op_sel:[1,0]
	v_pk_mul_f32 v[112:113], v[118:119], v[112:113] op_sel:[1,0]
	v_pk_mul_f32 v[114:115], v[118:119], v[114:115] op_sel:[1,0]
	v_lshlrev_b64 v[120:121], 11, v[120:121]
	v_readlane_b32 s7, v253, 5
	v_lshl_add_u64 v[120:121], s[6:7], 0, v[120:121]
	v_pk_fma_f32 v[108:109], v[160:161], v[108:109], v[156:157]
	v_pk_fma_f32 v[110:111], v[162:163], v[110:111], v[158:159]
	v_pk_fma_f32 v[112:113], v[148:149], v[112:113], v[152:153]
	v_pk_fma_f32 v[114:115], v[150:151], v[114:115], v[154:155]
	s_mov_b64 s[6:7], -1
	s_and_b64 vcc, exec, s[2:3]
	v_lshl_add_u64 v[120:121], v[198:199], 1, v[120:121]
.LBB0_486:
	s_andn2_b64 vcc, exec, s[6:7]
	v_lshl_add_u64 v[122:123], v[116:117], 2, s[52:53]
	s_cbranch_vccnz .LBB0_488
	v_lshl_add_u64 v[124:125], v[198:199], 2, v[122:123]
	global_store_dwordx4 v[124:125], v[108:111], off
	global_store_dwordx4 v[124:125], v[112:115], off offset:16
.LBB0_488:
	s_nop 0
	v_pk_add_f32 v[108:109], v[104:105], v[118:119] op_sel_hi:[1,0] neg_lo:[0,1] neg_hi:[0,1]
	v_pk_add_f32 v[104:105], v[100:101], v[118:119] op_sel_hi:[1,0] neg_lo:[0,1] neg_hi:[0,1]
	v_pk_add_f32 v[110:111], v[106:107], v[118:119] op_sel_hi:[1,0] neg_lo:[0,1] neg_hi:[0,1]
	v_pk_add_f32 v[106:107], v[102:103], v[118:119] op_sel_hi:[1,0] neg_lo:[0,1] neg_hi:[0,1]
	v_pk_mul_f32 v[100:101], v[118:119], v[108:109] op_sel:[1,0]
	v_pk_mul_f32 v[102:103], v[118:119], v[110:111] op_sel:[1,0]
	v_pk_mul_f32 v[104:105], v[118:119], v[104:105] op_sel:[1,0]
	v_pk_mul_f32 v[106:107], v[118:119], v[106:107] op_sel:[1,0]
	v_pk_fma_f32 v[100:101], v[140:141], v[100:101], v[144:145]
	v_pk_fma_f32 v[102:103], v[142:143], v[102:103], v[146:147]
	v_pk_fma_f32 v[104:105], v[132:133], v[104:105], v[136:137]
	v_pk_fma_f32 v[106:107], v[134:135], v[106:107], v[138:139]
	s_mov_b64 s[6:7], -1
	s_and_b64 vcc, exec, s[2:3]
.LBB0_492:
	s_andn2_b64 vcc, exec, s[6:7]
	s_cbranch_vccnz .LBB0_494
	v_lshl_add_u64 v[108:109], v[198:199], 2, v[122:123]
	global_store_dwordx4 v[108:109], v[100:103], off offset:512
	global_store_dwordx4 v[108:109], v[104:107], off offset:528
.LBB0_494:
	ds_read_b64 v[102:103], v32 offset:8448
	s_nop 0
	v_add3_u32 v104, s14, v233, 32
	v_ashrrev_i32_e32 v105, 31, v104
	v_readlane_b32 s6, v253, 4
	v_lshlrev_b64 v[100:101], 10, v[104:105]
	s_waitcnt lgkmcnt(0)
	v_cndmask_b32_e64 v103, v229, v103, s[100:101]
	v_pk_add_f32 v[106:107], v[96:97], v[102:103] op_sel_hi:[1,0] neg_lo:[0,1] neg_hi:[0,1]
	v_pk_add_f32 v[96:97], v[92:93], v[102:103] op_sel_hi:[1,0] neg_lo:[0,1] neg_hi:[0,1]
	v_pk_add_f32 v[108:109], v[98:99], v[102:103] op_sel_hi:[1,0] neg_lo:[0,1] neg_hi:[0,1]
	v_pk_add_f32 v[98:99], v[94:95], v[102:103] op_sel_hi:[1,0] neg_lo:[0,1] neg_hi:[0,1]
	v_pk_mul_f32 v[92:93], v[102:103], v[106:107] op_sel:[1,0]
	v_pk_mul_f32 v[94:95], v[102:103], v[108:109] op_sel:[1,0]
	v_pk_mul_f32 v[96:97], v[102:103], v[96:97] op_sel:[1,0]
	v_pk_mul_f32 v[98:99], v[102:103], v[98:99] op_sel:[1,0]
	v_lshlrev_b64 v[104:105], 11, v[104:105]
	v_readlane_b32 s7, v253, 5
	v_lshl_add_u64 v[104:105], s[6:7], 0, v[104:105]
	v_pk_fma_f32 v[92:93], v[160:161], v[92:93], v[156:157]
	v_pk_fma_f32 v[94:95], v[162:163], v[94:95], v[158:159]
	v_pk_fma_f32 v[96:97], v[148:149], v[96:97], v[152:153]
	v_pk_fma_f32 v[98:99], v[150:151], v[98:99], v[154:155]
	s_mov_b64 s[6:7], -1
	s_and_b64 vcc, exec, s[2:3]
	v_lshl_add_u64 v[104:105], v[198:199], 1, v[104:105]
.LBB0_498:
	s_andn2_b64 vcc, exec, s[6:7]
	v_lshl_add_u64 v[106:107], v[100:101], 2, s[52:53]
	s_cbranch_vccnz .LBB0_500
	v_lshl_add_u64 v[108:109], v[198:199], 2, v[106:107]
	global_store_dwordx4 v[108:109], v[92:95], off
	global_store_dwordx4 v[108:109], v[96:99], off offset:16
; template <unsigned D> __device__ __forceinline__ u32x4 rd8(u32x4 w) { w.x = rd<D>(w.x); w.y = rd<D>(w.y); w.z = rd<D>(w.z); w.w = rd<D>(w.w); return w; }
; __device__ __forceinline__ u32x4 pk8(const f32x4 v0, const f32x4 v1) { u32x4 w; w.x = pk_f16(v0[0], v0[1]); w.y = pk_f16(v0[2], v0[3]); w.z = pk_f16(v1[0], v1[1]); w.w = pk_f16(v1[2], v1[3]); return w; }
; __device__ __forceinline__ unsigned pk4_fp8(float a, float b, float c, float d) { int w = __builtin_amdgcn_cvt_pk_fp8_f32(a, b, 0, false); w = __builtin_amdgcn_cvt_pk_fp8_f32(c, d, w, true); return (unsigned)w; }
;     __device__ __forceinline__ void fused(f32x4 (&acc)[2][2][4][2], const GUnit& u, int wr, int wc, int fr, int fq, LAS unsigned char* lds, int wid, int lane) const {
;     ...
; #pragma unroll
;         for (int ai = 0; ai < 2; ++ai)
; #pragma unroll
;             for (int m = 0; m < 4; ++m) { const int r = ai * 128 + wr * 64 + m * 16 + fr; const f32x2 sr = S[r]; const size_t row = (size_t)(u.pm * 256 + r);
; #pragma unroll
;                 for (int bj = 0; bj < 2; ++bj) { const int col = gcol0 + bj * 128;
;                     f32x4 y0 = (acc[ai][bj][m][0] - sr.x) * sr.y * gv[bj][0] + bv[bj][0], y1 = (acc[ai][bj][m][1] - sr.x) * sr.y * gv[bj][1] + bv[bj][1];
;                     if (bad) { y0 = (f32x4){qnan, qnan, qnan, qnan}; y1 = y0; }
;                     if (last) { *(f32x4*)(out + row * 1024 + col) = y0; *(f32x4*)(out + row * 1024 + col + 4) = y1; }
;                     else { *(u32x4*)(H16 + row * 1024 + col) = rd8<D_H>(pk8(y0, y1));
;                            if (h8out) { u32x2 q8v; q8v.x = pk4_fp8(y0[0], y0[1], y0[2], y0[3]); q8v.y = pk4_fp8(y1[0], y1[1], y1[2], y1[3]); *(u32x2*)(ws + WS_H8 + row * 1024 + col) = q8v; } } }
;                 asm volatile("" ::: "memory"); }
.LBB0_500:
	s_nop 0
	v_pk_add_f32 v[92:93], v[88:89], v[102:103] op_sel_hi:[1,0] neg_lo:[0,1] neg_hi:[0,1]
	v_pk_add_f32 v[88:89], v[84:85], v[102:103] op_sel_hi:[1,0] neg_lo:[0,1] neg_hi:[0,1]
	v_pk_add_f32 v[94:95], v[90:91], v[102:103] op_sel_hi:[1,0] neg_lo:[0,1] neg_hi:[0,1]
	v_pk_add_f32 v[90:91], v[86:87], v[102:103] op_sel_hi:[1,0] neg_lo:[0,1] neg_hi:[0,1]
	v_pk_mul_f32 v[84:85], v[102:103], v[92:93] op_sel:[1,0]
	v_pk_mul_f32 v[86:87], v[102:103], v[94:95] op_sel:[1,0]
	v_pk_mul_f32 v[88:89], v[102:103], v[88:89] op_sel:[1,0]
	v_pk_mul_f32 v[90:91], v[102:103], v[90:91] op_sel:[1,0]
	v_pk_fma_f32 v[84:85], v[140:141], v[84:85], v[144:145]
	v_pk_fma_f32 v[86:87], v[142:143], v[86:87], v[146:147]
	v_pk_fma_f32 v[88:89], v[132:133], v[88:89], v[136:137]
	v_pk_fma_f32 v[90:91], v[134:135], v[90:91], v[138:139]
	s_mov_b64 s[6:7], -1
	s_and_b64 vcc, exec, s[2:3]
.LBB0_504:
	s_andn2_b64 vcc, exec, s[6:7]
	s_cbranch_vccnz .LBB0_506
	v_lshl_add_u64 v[92:93], v[198:199], 2, v[106:107]
	global_store_dwordx4 v[92:93], v[84:87], off offset:512
	global_store_dwordx4 v[92:93], v[88:91], off offset:528
.LBB0_506:
	ds_read_b64 v[86:87], v32 offset:8576
	s_nop 0
	v_add3_u32 v88, s14, v233, 48
	v_ashrrev_i32_e32 v89, 31, v88
	v_readlane_b32 s6, v253, 4
	v_lshlrev_b64 v[84:85], 10, v[88:89]
	s_waitcnt lgkmcnt(0)
	v_cndmask_b32_e64 v87, v229, v87, s[100:101]
	v_pk_add_f32 v[90:91], v[80:81], v[86:87] op_sel_hi:[1,0] neg_lo:[0,1] neg_hi:[0,1]
	v_pk_add_f32 v[80:81], v[76:77], v[86:87] op_sel_hi:[1,0] neg_lo:[0,1] neg_hi:[0,1]
	v_pk_add_f32 v[92:93], v[82:83], v[86:87] op_sel_hi:[1,0] neg_lo:[0,1] neg_hi:[0,1]
	v_pk_add_f32 v[82:83], v[78:79], v[86:87] op_sel_hi:[1,0] neg_lo:[0,1] neg_hi:[0,1]
	v_pk_mul_f32 v[76:77], v[86:87], v[90:91] op_sel:[1,0]
	v_pk_mul_f32 v[78:79], v[86:87], v[92:93] op_sel:[1,0]
	v_pk_mul_f32 v[80:81], v[86:87], v[80:81] op_sel:[1,0]
	v_pk_mul_f32 v[82:83], v[86:87], v[82:83] op_sel:[1,0]
	v_lshlrev_b64 v[88:89], 11, v[88:89]
	v_readlane_b32 s7, v253, 5
	v_lshl_add_u64 v[88:89], s[6:7], 0, v[88:89]
	v_pk_fma_f32 v[76:77], v[160:161], v[76:77], v[156:157]
	v_pk_fma_f32 v[78:79], v[162:163], v[78:79], v[158:159]
	v_pk_fma_f32 v[80:81], v[148:149], v[80:81], v[152:153]
	v_pk_fma_f32 v[82:83], v[150:151], v[82:83], v[154:155]
	s_mov_b64 s[6:7], -1
	s_and_b64 vcc, exec, s[2:3]
	v_lshl_add_u64 v[88:89], v[198:199], 1, v[88:89]
	v_mov_b32_e32 v233, v226
.LBB0_510:
	s_andn2_b64 vcc, exec, s[6:7]
	v_lshl_add_u64 v[90:91], v[84:85], 2, s[52:53]
	s_cbranch_vccnz .LBB0_512
	v_lshl_add_u64 v[92:93], v[198:199], 2, v[90:91]
	global_store_dwordx4 v[92:93], v[76:79], off
	global_store_dwordx4 v[92:93], v[80:83], off offset:16
.LBB0_512:
	s_nop 0
	v_pk_add_f32 v[76:77], v[72:73], v[86:87] op_sel_hi:[1,0] neg_lo:[0,1] neg_hi:[0,1]
	v_pk_add_f32 v[72:73], v[68:69], v[86:87] op_sel_hi:[1,0] neg_lo:[0,1] neg_hi:[0,1]
	v_pk_add_f32 v[78:79], v[74:75], v[86:87] op_sel_hi:[1,0] neg_lo:[0,1] neg_hi:[0,1]
	v_pk_add_f32 v[74:75], v[70:71], v[86:87] op_sel_hi:[1,0] neg_lo:[0,1] neg_hi:[0,1]
	v_pk_mul_f32 v[68:69], v[86:87], v[76:77] op_sel:[1,0]
	v_pk_mul_f32 v[70:71], v[86:87], v[78:79] op_sel:[1,0]
	v_pk_mul_f32 v[72:73], v[86:87], v[72:73] op_sel:[1,0]
	v_pk_mul_f32 v[74:75], v[86:87], v[74:75] op_sel:[1,0]
	v_pk_fma_f32 v[68:69], v[140:141], v[68:69], v[144:145]
	v_pk_fma_f32 v[70:71], v[142:143], v[70:71], v[146:147]
	v_pk_fma_f32 v[72:73], v[132:133], v[72:73], v[136:137]
	v_pk_fma_f32 v[74:75], v[134:135], v[74:75], v[138:139]
	s_mov_b64 s[6:7], -1
	s_and_b64 vcc, exec, s[2:3]
.LBB0_516:
	s_andn2_b64 vcc, exec, s[6:7]
	s_cbranch_vccnz .LBB0_518
	v_lshl_add_u64 v[76:77], v[198:199], 2, v[90:91]
	global_store_dwordx4 v[76:77], v[68:71], off offset:512
	global_store_dwordx4 v[76:77], v[72:75], off offset:528
.LBB0_518:
	ds_read_b64 v[70:71], v32 offset:9216
	v_readlane_b32 s6, v253, 4
	v_readlane_b32 s7, v253, 5
	v_lshlrev_b64 v[68:69], 10, v[212:213]
	s_and_b64 vcc, exec, s[2:3]
	s_waitcnt lgkmcnt(0)
	v_cndmask_b32_e64 v71, v229, v71, s[100:101]
	v_pk_add_f32 v[74:75], v[64:65], v[70:71] op_sel_hi:[1,0] neg_lo:[0,1] neg_hi:[0,1]
	v_pk_add_f32 v[64:65], v[60:61], v[70:71] op_sel_hi:[1,0] neg_lo:[0,1] neg_hi:[0,1]
	v_pk_add_f32 v[76:77], v[66:67], v[70:71] op_sel_hi:[1,0] neg_lo:[0,1] neg_hi:[0,1]
	v_pk_add_f32 v[66:67], v[62:63], v[70:71] op_sel_hi:[1,0] neg_lo:[0,1] neg_hi:[0,1]
	v_pk_mul_f32 v[60:61], v[70:71], v[74:75] op_sel:[1,0]
	v_pk_mul_f32 v[62:63], v[70:71], v[76:77] op_sel:[1,0]
	v_pk_mul_f32 v[64:65], v[70:71], v[64:65] op_sel:[1,0]
	v_pk_mul_f32 v[66:67], v[70:71], v[66:67] op_sel:[1,0]
	v_lshl_add_u64 v[72:73], s[6:7], 0, v[210:211]
	v_pk_fma_f32 v[60:61], v[160:161], v[60:61], v[156:157]
	v_pk_fma_f32 v[62:63], v[162:163], v[62:63], v[158:159]
	v_pk_fma_f32 v[64:65], v[148:149], v[64:65], v[152:153]
	v_pk_fma_f32 v[66:67], v[150:151], v[66:67], v[154:155]
	s_mov_b64 s[6:7], -1
	v_lshl_add_u64 v[72:73], v[198:199], 1, v[72:73]
.LBB0_522:
	s_andn2_b64 vcc, exec, s[6:7]
	v_lshl_add_u64 v[74:75], v[68:69], 2, s[52:53]
	s_cbranch_vccnz .LBB0_524
	v_lshl_add_u64 v[76:77], v[198:199], 2, v[74:75]
	global_store_dwordx4 v[76:77], v[60:63], off
	global_store_dwordx4 v[76:77], v[64:67], off offset:16
.LBB0_524:
	s_nop 0
	v_pk_add_f32 v[60:61], v[56:57], v[70:71] op_sel_hi:[1,0] neg_lo:[0,1] neg_hi:[0,1]
	v_pk_add_f32 v[56:57], v[52:53], v[70:71] op_sel_hi:[1,0] neg_lo:[0,1] neg_hi:[0,1]
	v_pk_add_f32 v[62:63], v[58:59], v[70:71] op_sel_hi:[1,0] neg_lo:[0,1] neg_hi:[0,1]
	v_pk_add_f32 v[58:59], v[54:55], v[70:71] op_sel_hi:[1,0] neg_lo:[0,1] neg_hi:[0,1]
	v_pk_mul_f32 v[52:53], v[70:71], v[60:61] op_sel:[1,0]
	v_pk_mul_f32 v[54:55], v[70:71], v[62:63] op_sel:[1,0]
	v_pk_mul_f32 v[56:57], v[70:71], v[56:57] op_sel:[1,0]
	v_pk_mul_f32 v[58:59], v[70:71], v[58:59] op_sel:[1,0]
	v_pk_fma_f32 v[52:53], v[140:141], v[52:53], v[144:145]
	v_pk_fma_f32 v[54:55], v[142:143], v[54:55], v[146:147]
	v_pk_fma_f32 v[56:57], v[132:133], v[56:57], v[136:137]
	v_pk_fma_f32 v[58:59], v[134:135], v[58:59], v[138:139]
	s_mov_b64 s[6:7], -1
	s_and_b64 vcc, exec, s[2:3]
; template <unsigned D> __device__ __forceinline__ u32x4 rd8(u32x4 w) { w.x = rd<D>(w.x); w.y = rd<D>(w.y); w.z = rd<D>(w.z); w.w = rd<D>(w.w); return w; }
; __device__ __forceinline__ u32x4 pk8(const f32x4 v0, const f32x4 v1) { u32x4 w; w.x = pk_f16(v0[0], v0[1]); w.y = pk_f16(v0[2], v0[3]); w.z = pk_f16(v1[0], v1[1]); w.w = pk_f16(v1[2], v1[3]); return w; }
; __device__ __forceinline__ unsigned pk4_fp8(float a, float b, float c, float d) { int w = __builtin_amdgcn_cvt_pk_fp8_f32(a, b, 0, false); w = __builtin_amdgcn_cvt_pk_fp8_f32(c, d, w, true); return (unsigned)w; }
;     __device__ __forceinline__ void fused(f32x4 (&acc)[2][2][4][2], const GUnit& u, int wr, int wc, int fr, int fq, LAS unsigned char* lds, int wid, int lane) const {
;     ...
; #pragma unroll
;         for (int ai = 0; ai < 2; ++ai)
; #pragma unroll
;             for (int m = 0; m < 4; ++m) { const int r = ai * 128 + wr * 64 + m * 16 + fr; const f32x2 sr = S[r]; const size_t row = (size_t)(u.pm * 256 + r);
; #pragma unroll
;                 for (int bj = 0; bj < 2; ++bj) { const int col = gcol0 + bj * 128;
;                     f32x4 y0 = (acc[ai][bj][m][0] - sr.x) * sr.y * gv[bj][0] + bv[bj][0], y1 = (acc[ai][bj][m][1] - sr.x) * sr.y * gv[bj][1] + bv[bj][1];
;                     if (bad) { y0 = (f32x4){qnan, qnan, qnan, qnan}; y1 = y0; }
;                     if (last) { *(f32x4*)(out + row * 1024 + col) = y0; *(f32x4*)(out + row * 1024 + col + 4) = y1; }
;                     else { *(u32x4*)(H16 + row * 1024 + col) = rd8<D_H>(pk8(y0, y1));
;                            if (h8out) { u32x2 q8v; q8v.x = pk4_fp8(y0[0], y0[1], y0[2], y0[3]); q8v.y = pk4_fp8(y1[0], y1[1], y1[2], y1[3]); *(u32x2*)(ws + WS_H8 + row * 1024 + col) = q8v; } } }
;                 asm volatile("" ::: "memory"); }
.LBB0_528:
	s_andn2_b64 vcc, exec, s[6:7]
	s_cbranch_vccnz .LBB0_530
	v_lshl_add_u64 v[60:61], v[198:199], 2, v[74:75]
	global_store_dwordx4 v[60:61], v[52:55], off offset:512
	global_store_dwordx4 v[60:61], v[56:59], off offset:528
.LBB0_530:
	ds_read_b64 v[54:55], v32 offset:9344
	v_readlane_b32 s6, v253, 4
	v_readlane_b32 s7, v253, 5
	v_lshlrev_b64 v[52:53], 10, v[208:209]
	s_and_b64 vcc, exec, s[2:3]
	s_waitcnt lgkmcnt(0)
	v_cndmask_b32_e64 v55, v229, v55, s[100:101]
	v_pk_add_f32 v[56:57], v[48:49], v[54:55] op_sel_hi:[1,0] neg_lo:[0,1] neg_hi:[0,1]
	v_pk_add_f32 v[48:49], v[44:45], v[54:55] op_sel_hi:[1,0] neg_lo:[0,1] neg_hi:[0,1]
	v_pk_add_f32 v[58:59], v[50:51], v[54:55] op_sel_hi:[1,0] neg_lo:[0,1] neg_hi:[0,1]
	v_pk_add_f32 v[50:51], v[46:47], v[54:55] op_sel_hi:[1,0] neg_lo:[0,1] neg_hi:[0,1]
	v_pk_mul_f32 v[44:45], v[54:55], v[56:57] op_sel:[1,0]
	v_pk_mul_f32 v[46:47], v[54:55], v[58:59] op_sel:[1,0]
	v_pk_mul_f32 v[48:49], v[54:55], v[48:49] op_sel:[1,0]
	v_pk_mul_f32 v[50:51], v[54:55], v[50:51] op_sel:[1,0]
	v_lshl_add_u64 v[34:35], s[6:7], 0, v[34:35]
	v_pk_fma_f32 v[44:45], v[160:161], v[44:45], v[156:157]
	v_pk_fma_f32 v[46:47], v[162:163], v[46:47], v[158:159]
	v_pk_fma_f32 v[48:49], v[148:149], v[48:49], v[152:153]
	v_pk_fma_f32 v[50:51], v[150:151], v[50:51], v[154:155]
	s_mov_b64 s[6:7], -1
	v_lshl_add_u64 v[56:57], v[198:199], 1, v[34:35]
.LBB0_534:
	s_andn2_b64 vcc, exec, s[6:7]
	v_lshl_add_u64 v[58:59], v[52:53], 2, s[52:53]
	s_cbranch_vccnz .LBB0_536
	v_lshl_add_u64 v[34:35], v[198:199], 2, v[58:59]
	global_store_dwordx4 v[34:35], v[44:47], off
	global_store_dwordx4 v[34:35], v[48:51], off offset:16
.LBB0_536:
	v_pk_add_f32 v[34:35], v[40:41], v[54:55] op_sel_hi:[1,0] neg_lo:[0,1] neg_hi:[0,1]
	v_pk_add_f32 v[40:41], v[38:39], v[54:55] op_sel_hi:[1,0] neg_lo:[0,1] neg_hi:[0,1]
	v_pk_add_f32 v[38:39], v[36:37], v[54:55] op_sel_hi:[1,0] neg_lo:[0,1] neg_hi:[0,1]
	v_pk_add_f32 v[36:37], v[42:43], v[54:55] op_sel_hi:[1,0] neg_lo:[0,1] neg_hi:[0,1]
	v_pk_mul_f32 v[34:35], v[54:55], v[34:35] op_sel:[1,0]
	v_pk_mul_f32 v[36:37], v[54:55], v[36:37] op_sel:[1,0]
	v_pk_mul_f32 v[38:39], v[54:55], v[38:39] op_sel:[1,0]
	v_pk_mul_f32 v[40:41], v[54:55], v[40:41] op_sel:[1,0]
	v_pk_fma_f32 v[34:35], v[140:141], v[34:35], v[144:145]
	v_pk_fma_f32 v[36:37], v[142:143], v[36:37], v[146:147]
	v_pk_fma_f32 v[38:39], v[132:133], v[38:39], v[136:137]
	v_pk_fma_f32 v[40:41], v[134:135], v[40:41], v[138:139]
	s_mov_b64 s[6:7], -1
	s_and_b64 vcc, exec, s[2:3]
.LBB0_540:
	s_andn2_b64 vcc, exec, s[6:7]
	s_cbranch_vccnz .LBB0_542
	v_lshl_add_u64 v[42:43], v[198:199], 2, v[58:59]
	global_store_dwordx4 v[42:43], v[34:37], off offset:512
	global_store_dwordx4 v[42:43], v[38:41], off offset:528
.LBB0_542:
	ds_read_b64 v[36:37], v32 offset:9472
	v_readlane_b32 s6, v253, 4
	v_readlane_b32 s7, v253, 5
	v_lshlrev_b64 v[34:35], 10, v[206:207]
	s_and_b64 vcc, exec, s[2:3]
	s_waitcnt lgkmcnt(0)
	v_cndmask_b32_e64 v37, v229, v37, s[100:101]
	v_pk_add_f32 v[40:41], v[28:29], v[36:37] op_sel_hi:[1,0] neg_lo:[0,1] neg_hi:[0,1]
	v_pk_add_f32 v[28:29], v[24:25], v[36:37] op_sel_hi:[1,0] neg_lo:[0,1] neg_hi:[0,1]
	v_pk_add_f32 v[42:43], v[30:31], v[36:37] op_sel_hi:[1,0] neg_lo:[0,1] neg_hi:[0,1]
	v_pk_add_f32 v[30:31], v[26:27], v[36:37] op_sel_hi:[1,0] neg_lo:[0,1] neg_hi:[0,1]
	v_pk_mul_f32 v[24:25], v[36:37], v[40:41] op_sel:[1,0]
	v_pk_mul_f32 v[26:27], v[36:37], v[42:43] op_sel:[1,0]
	v_pk_mul_f32 v[28:29], v[36:37], v[28:29] op_sel:[1,0]
	v_pk_mul_f32 v[30:31], v[36:37], v[30:31] op_sel:[1,0]
	v_lshl_add_u64 v[38:39], s[6:7], 0, v[204:205]
	v_pk_fma_f32 v[24:25], v[160:161], v[24:25], v[156:157]
	v_pk_fma_f32 v[26:27], v[162:163], v[26:27], v[158:159]
	v_pk_fma_f32 v[28:29], v[148:149], v[28:29], v[152:153]
	v_pk_fma_f32 v[30:31], v[150:151], v[30:31], v[154:155]
	s_mov_b64 s[6:7], -1
	v_lshl_add_u64 v[38:39], v[198:199], 1, v[38:39]
; template <unsigned D> __device__ __forceinline__ u32x4 rd8(u32x4 w) { w.x = rd<D>(w.x); w.y = rd<D>(w.y); w.z = rd<D>(w.z); w.w = rd<D>(w.w); return w; }
; __device__ __forceinline__ u32x4 pk8(const f32x4 v0, const f32x4 v1) { u32x4 w; w.x = pk_f16(v0[0], v0[1]); w.y = pk_f16(v0[2], v0[3]); w.z = pk_f16(v1[0], v1[1]); w.w = pk_f16(v1[2], v1[3]); return w; }
; __device__ __forceinline__ unsigned pk4_fp8(float a, float b, float c, float d) { int w = __builtin_amdgcn_cvt_pk_fp8_f32(a, b, 0, false); w = __builtin_amdgcn_cvt_pk_fp8_f32(c, d, w, true); return (unsigned)w; }
;     __device__ __forceinline__ void fused(f32x4 (&acc)[2][2][4][2], const GUnit& u, int wr, int wc, int fr, int fq, LAS unsigned char* lds, int wid, int lane) const {
;     ...
; #pragma unroll
;         for (int ai = 0; ai < 2; ++ai)
; #pragma unroll
;             for (int m = 0; m < 4; ++m) { const int r = ai * 128 + wr * 64 + m * 16 + fr; const f32x2 sr = S[r]; const size_t row = (size_t)(u.pm * 256 + r);
; #pragma unroll
;                 for (int bj = 0; bj < 2; ++bj) { const int col = gcol0 + bj * 128;
;                     f32x4 y0 = (acc[ai][bj][m][0] - sr.x) * sr.y * gv[bj][0] + bv[bj][0], y1 = (acc[ai][bj][m][1] - sr.x) * sr.y * gv[bj][1] + bv[bj][1];
;                     if (bad) { y0 = (f32x4){qnan, qnan, qnan, qnan}; y1 = y0; }
;                     if (last) { *(f32x4*)(out + row * 1024 + col) = y0; *(f32x4*)(out + row * 1024 + col + 4) = y1; }
;                     else { *(u32x4*)(H16 + row * 1024 + col) = rd8<D_H>(pk8(y0, y1));
;                            if (h8out) { u32x2 q8v; q8v.x = pk4_fp8(y0[0], y0[1], y0[2], y0[3]); q8v.y = pk4_fp8(y1[0], y1[1], y1[2], y1[3]); *(u32x2*)(ws + WS_H8 + row * 1024 + col) = q8v; } } }
;                 asm volatile("" ::: "memory"); }
.LBB0_546:
	s_andn2_b64 vcc, exec, s[6:7]
	v_lshl_add_u64 v[40:41], v[34:35], 2, s[52:53]
	s_cbranch_vccnz .LBB0_548
	v_lshl_add_u64 v[42:43], v[198:199], 2, v[40:41]
	global_store_dwordx4 v[42:43], v[24:27], off
	global_store_dwordx4 v[42:43], v[28:31], off offset:16
.LBB0_548:
	s_nop 0
	v_pk_add_f32 v[24:25], v[20:21], v[36:37] op_sel_hi:[1,0] neg_lo:[0,1] neg_hi:[0,1]
	v_pk_add_f32 v[20:21], v[16:17], v[36:37] op_sel_hi:[1,0] neg_lo:[0,1] neg_hi:[0,1]
	v_pk_add_f32 v[26:27], v[22:23], v[36:37] op_sel_hi:[1,0] neg_lo:[0,1] neg_hi:[0,1]
	v_pk_add_f32 v[22:23], v[18:19], v[36:37] op_sel_hi:[1,0] neg_lo:[0,1] neg_hi:[0,1]
	v_pk_mul_f32 v[16:17], v[36:37], v[24:25] op_sel:[1,0]
	v_pk_mul_f32 v[18:19], v[36:37], v[26:27] op_sel:[1,0]
	v_pk_mul_f32 v[20:21], v[36:37], v[20:21] op_sel:[1,0]
	v_pk_mul_f32 v[22:23], v[36:37], v[22:23] op_sel:[1,0]
	v_pk_fma_f32 v[16:17], v[140:141], v[16:17], v[144:145]
	v_pk_fma_f32 v[18:19], v[142:143], v[18:19], v[146:147]
	v_pk_fma_f32 v[20:21], v[132:133], v[20:21], v[136:137]
	v_pk_fma_f32 v[22:23], v[134:135], v[22:23], v[138:139]
	s_mov_b64 s[6:7], -1
	s_and_b64 vcc, exec, s[2:3]
.LBB0_552:
	s_andn2_b64 vcc, exec, s[6:7]
	s_cbranch_vccnz .LBB0_554
	v_lshl_add_u64 v[24:25], v[198:199], 2, v[40:41]
	global_store_dwordx4 v[24:25], v[16:19], off offset:512
	global_store_dwordx4 v[24:25], v[20:23], off offset:528
.LBB0_554:
	ds_read_b64 v[18:19], v32 offset:9600
	v_readlane_b32 s6, v253, 4
	v_readlane_b32 s7, v253, 5
	v_lshlrev_b64 v[16:17], 10, v[200:201]
	s_and_b64 vcc, exec, s[2:3]
	s_waitcnt lgkmcnt(0)
	v_cndmask_b32_e64 v19, v229, v19, s[100:101]
	v_pk_add_f32 v[22:23], v[12:13], v[18:19] op_sel_hi:[1,0] neg_lo:[0,1] neg_hi:[0,1]
	v_pk_add_f32 v[12:13], v[8:9], v[18:19] op_sel_hi:[1,0] neg_lo:[0,1] neg_hi:[0,1]
	v_pk_add_f32 v[24:25], v[14:15], v[18:19] op_sel_hi:[1,0] neg_lo:[0,1] neg_hi:[0,1]
	v_pk_add_f32 v[14:15], v[10:11], v[18:19] op_sel_hi:[1,0] neg_lo:[0,1] neg_hi:[0,1]
	v_pk_mul_f32 v[8:9], v[18:19], v[22:23] op_sel:[1,0]
	v_pk_mul_f32 v[10:11], v[18:19], v[24:25] op_sel:[1,0]
	v_pk_mul_f32 v[12:13], v[18:19], v[12:13] op_sel:[1,0]
	v_pk_mul_f32 v[14:15], v[18:19], v[14:15] op_sel:[1,0]
	v_lshl_add_u64 v[20:21], s[6:7], 0, v[202:203]
	v_pk_fma_f32 v[8:9], v[160:161], v[8:9], v[156:157]
	v_pk_fma_f32 v[10:11], v[162:163], v[10:11], v[158:159]
	v_pk_fma_f32 v[12:13], v[148:149], v[12:13], v[152:153]
	v_pk_fma_f32 v[14:15], v[150:151], v[14:15], v[154:155]
	s_mov_b64 s[6:7], -1
	v_lshl_add_u64 v[20:21], v[198:199], 1, v[20:21]
.LBB0_558:
	s_andn2_b64 vcc, exec, s[6:7]
	v_lshl_add_u64 v[22:23], v[16:17], 2, s[52:53]
	s_cbranch_vccnz .LBB0_560
	v_lshl_add_u64 v[24:25], v[198:199], 2, v[22:23]
	global_store_dwordx4 v[24:25], v[8:11], off
	global_store_dwordx4 v[24:25], v[12:15], off offset:16
.LBB0_560:
	s_nop 0
	v_pk_add_f32 v[8:9], v[4:5], v[18:19] op_sel_hi:[1,0] neg_lo:[0,1] neg_hi:[0,1]
	v_pk_add_f32 v[4:5], v[0:1], v[18:19] op_sel_hi:[1,0] neg_lo:[0,1] neg_hi:[0,1]
	v_pk_add_f32 v[10:11], v[6:7], v[18:19] op_sel_hi:[1,0] neg_lo:[0,1] neg_hi:[0,1]
	v_pk_add_f32 v[6:7], v[2:3], v[18:19] op_sel_hi:[1,0] neg_lo:[0,1] neg_hi:[0,1]
	v_pk_mul_f32 v[0:1], v[18:19], v[8:9] op_sel:[1,0]
	v_pk_mul_f32 v[2:3], v[18:19], v[10:11] op_sel:[1,0]
	v_pk_mul_f32 v[4:5], v[18:19], v[4:5] op_sel:[1,0]
	v_pk_mul_f32 v[6:7], v[18:19], v[6:7] op_sel:[1,0]
	v_pk_fma_f32 v[0:1], v[140:141], v[0:1], v[144:145]
	v_pk_fma_f32 v[2:3], v[142:143], v[2:3], v[146:147]
	v_pk_fma_f32 v[4:5], v[132:133], v[4:5], v[136:137]
	v_pk_fma_f32 v[6:7], v[134:135], v[6:7], v[138:139]
	s_mov_b64 s[4:5], -1
	s_and_b64 vcc, exec, s[2:3]
.LBB0_564:
	s_andn2_b64 vcc, exec, s[4:5]
	s_cbranch_vccnz .LBB0_566
	v_lshl_add_u64 v[8:9], v[198:199], 2, v[22:23]
	global_store_dwordx4 v[8:9], v[0:3], off offset:512
	global_store_dwordx4 v[8:9], v[4:7], off offset:528
